# K-loops: s_setprio toggles removed + duplicate lgkmcnt(0) removed + s_nop before 2nd DMA replaced by reordering m0 write ahead of the address VALU
# baseline (speedup 1.0000x reference)
.LBB0_267:
	s_add_u32 s12, s4, 0xfffc0080
	s_addc_u32 s13, s5, -1
	s_add_i32 s86, 0, 0x10000
	v_add_u32_e32 v0, s86, v150
	ds_read_b128 v[142:145], v0
	ds_read_b128 v[146:149], v0 offset:1024
	ds_read_b128 v[152:155], v0 offset:2048
	ds_read_b128 v[156:159], v0 offset:3072
	s_cmp_eq_u32 s85, 12
	s_cselect_b32 s15, s44, s13
	s_cselect_b32 s14, s45, s12
	s_cselect_b32 s13, s47, s79
	s_cselect_b32 s12, s55, s78
	v_lshl_add_u64 v[194:195], s[4:5], 0, v[138:139]
	s_add_i32 m0, s7, 0xc000
	ds_read_b128 v[160:163], v151
	ds_read_b128 v[164:167], v151 offset:1024
	ds_read_b128 v[168:171], v151 offset:2048
	ds_read_b128 v[172:175], v151 offset:3072
	ds_read_b128 v[176:179], v151 offset:4096
	ds_read_b128 v[180:183], v151 offset:5120
	ds_read_b128 v[184:187], v151 offset:6144
	ds_read_b128 v[190:193], v151 offset:7168
	global_load_lds_dwordx4 v[194:195], off
	s_add_i32 m0, s7, 0xe000
	v_lshl_add_u64 v[194:195], s[4:5], 0, v[140:141]
	global_load_lds_dwordx4 v[194:195], off
	s_waitcnt lgkmcnt(8)
	s_barrier
	s_waitcnt lgkmcnt(0)
	v_mfma_f32_16x16x32_bf16 v[126:129], v[142:145], v[160:163], v[126:129]
	v_mfma_f32_16x16x32_bf16 v[122:125], v[152:155], v[160:163], v[122:125]
	v_mfma_f32_16x16x32_bf16 v[110:113], v[142:145], v[168:171], v[110:113]
	v_mfma_f32_16x16x32_bf16 v[106:109], v[152:155], v[168:171], v[106:109]
	v_mfma_f32_16x16x32_bf16 v[94:97], v[142:145], v[176:179], v[94:97]
	v_mfma_f32_16x16x32_bf16 v[90:93], v[152:155], v[176:179], v[90:93]
	v_mfma_f32_16x16x32_bf16 v[78:81], v[142:145], v[184:187], v[78:81]
	v_mfma_f32_16x16x32_bf16 v[74:77], v[152:155], v[184:187], v[74:77]
	v_mfma_f32_16x16x32_bf16 v[126:129], v[146:149], v[164:167], v[126:129]
	v_mfma_f32_16x16x32_bf16 v[122:125], v[156:159], v[164:167], v[122:125]
	v_mfma_f32_16x16x32_bf16 v[110:113], v[146:149], v[172:175], v[110:113]
	v_mfma_f32_16x16x32_bf16 v[106:109], v[156:159], v[172:175], v[106:109]
	v_mfma_f32_16x16x32_bf16 v[94:97], v[146:149], v[180:183], v[94:97]
	v_mfma_f32_16x16x32_bf16 v[90:93], v[156:159], v[180:183], v[90:93]
	v_mfma_f32_16x16x32_bf16 v[78:81], v[146:149], v[190:193], v[78:81]
	v_mfma_f32_16x16x32_bf16 v[74:77], v[156:159], v[190:193], v[74:77]
	s_barrier
	s_add_i32 s88, 0, 0x14000
	s_add_i32 s86, s86, s22
	v_add_u32_e32 v0, s88, v150
	v_lshl_add_u64 v[210:211], s[12:13], 0, v[134:135]
	s_mov_b32 m0, s86
	ds_read_b128 v[194:197], v0
	ds_read_b128 v[198:201], v0 offset:1024
	ds_read_b128 v[202:205], v0 offset:2048
	ds_read_b128 v[206:209], v0 offset:3072
	global_load_lds_dwordx4 v[210:211], off
	s_add_i32 m0, s86, 0x2000
	v_lshl_add_u64 v[212:213], s[12:13], 0, v[130:131]
	global_load_lds_dwordx4 v[212:213], off
	s_barrier
	s_waitcnt lgkmcnt(0)
	v_mfma_f32_16x16x32_bf16 v[118:121], v[194:197], v[160:163], v[118:121]
	v_mfma_f32_16x16x32_bf16 v[114:117], v[202:205], v[160:163], v[114:117]
	v_mfma_f32_16x16x32_bf16 v[102:105], v[194:197], v[168:171], v[102:105]
	v_mfma_f32_16x16x32_bf16 v[98:101], v[202:205], v[168:171], v[98:101]
	v_mfma_f32_16x16x32_bf16 v[86:89], v[194:197], v[176:179], v[86:89]
	v_mfma_f32_16x16x32_bf16 v[82:85], v[202:205], v[176:179], v[82:85]
	v_mfma_f32_16x16x32_bf16 v[70:73], v[194:197], v[184:187], v[70:73]
	v_mfma_f32_16x16x32_bf16 v[66:69], v[202:205], v[184:187], v[66:69]
	v_mfma_f32_16x16x32_bf16 v[118:121], v[198:201], v[164:167], v[118:121]
	v_mfma_f32_16x16x32_bf16 v[114:117], v[206:209], v[164:167], v[114:117]
	v_mfma_f32_16x16x32_bf16 v[102:105], v[198:201], v[172:175], v[102:105]
	v_mfma_f32_16x16x32_bf16 v[98:101], v[206:209], v[172:175], v[98:101]
	v_mfma_f32_16x16x32_bf16 v[86:89], v[198:201], v[180:183], v[86:89]
	v_mfma_f32_16x16x32_bf16 v[82:85], v[206:209], v[180:183], v[82:85]
	v_mfma_f32_16x16x32_bf16 v[70:73], v[198:201], v[190:193], v[70:73]
	v_mfma_f32_16x16x32_bf16 v[66:69], v[206:209], v[190:193], v[66:69]
	s_mov_b32 m0, s7
	v_lshl_add_u64 v[214:215], s[14:15], 0, v[136:137]
	s_barrier
	ds_read_b128 v[160:163], v151 offset:16384
	ds_read_b128 v[164:167], v151 offset:17408
	ds_read_b128 v[168:171], v151 offset:18432
	ds_read_b128 v[172:175], v151 offset:19456
	ds_read_b128 v[176:179], v151 offset:20480
	ds_read_b128 v[180:183], v151 offset:21504
	ds_read_b128 v[184:187], v151 offset:22528
	ds_read_b128 v[190:193], v151 offset:23552
	global_load_lds_dwordx4 v[214:215], off
	s_mov_b32 m0, s23
	v_lshl_add_u64 v[216:217], s[14:15], 0, v[132:133]
	global_load_lds_dwordx4 v[216:217], off
	s_barrier
	s_waitcnt lgkmcnt(0)
	v_mfma_f32_16x16x32_bf16 v[62:65], v[142:145], v[160:163], v[62:65]
	v_mfma_f32_16x16x32_bf16 v[58:61], v[152:155], v[160:163], v[58:61]
	v_mfma_f32_16x16x32_bf16 v[46:49], v[142:145], v[168:171], v[46:49]
	v_mfma_f32_16x16x32_bf16 v[42:45], v[152:155], v[168:171], v[42:45]
	v_mfma_f32_16x16x32_bf16 v[30:33], v[142:145], v[176:179], v[30:33]
	v_mfma_f32_16x16x32_bf16 v[26:29], v[152:155], v[176:179], v[26:29]
	v_mfma_f32_16x16x32_bf16 v[14:17], v[142:145], v[184:187], v[14:17]
	v_mfma_f32_16x16x32_bf16 v[10:13], v[152:155], v[184:187], v[10:13]
	v_mfma_f32_16x16x32_bf16 v[62:65], v[146:149], v[164:167], v[62:65]
	v_mfma_f32_16x16x32_bf16 v[58:61], v[156:159], v[164:167], v[58:61]
	v_mfma_f32_16x16x32_bf16 v[46:49], v[146:149], v[172:175], v[46:49]
	v_mfma_f32_16x16x32_bf16 v[42:45], v[156:159], v[172:175], v[42:45]
	v_mfma_f32_16x16x32_bf16 v[30:33], v[146:149], v[180:183], v[30:33]
	v_mfma_f32_16x16x32_bf16 v[26:29], v[156:159], v[180:183], v[26:29]
	v_mfma_f32_16x16x32_bf16 v[14:17], v[146:149], v[190:193], v[14:17]
	v_mfma_f32_16x16x32_bf16 v[10:13], v[156:159], v[190:193], v[10:13]
	s_barrier
	s_add_u32 s86, s12, 0x40000
	s_addc_u32 s87, s13, 0
	s_add_i32 s88, s88, s22
	s_mov_b32 m0, s88
	v_lshl_add_u64 v[142:143], s[86:87], 0, v[134:135]
	global_load_lds_dwordx4 v[142:143], off
	s_add_i32 m0, s88, 0x2000
	v_lshl_add_u64 v[142:143], s[86:87], 0, v[130:131]
	global_load_lds_dwordx4 v[142:143], off
	s_waitcnt vmcnt(6)
	s_barrier
	v_mfma_f32_16x16x32_bf16 v[54:57], v[194:197], v[160:163], v[54:57]
	v_mfma_f32_16x16x32_bf16 v[50:53], v[202:205], v[160:163], v[50:53]
	v_mfma_f32_16x16x32_bf16 v[38:41], v[194:197], v[168:171], v[38:41]
	v_mfma_f32_16x16x32_bf16 v[34:37], v[202:205], v[168:171], v[34:37]
	v_mfma_f32_16x16x32_bf16 v[22:25], v[194:197], v[176:179], v[22:25]
	v_mfma_f32_16x16x32_bf16 v[18:21], v[202:205], v[176:179], v[18:21]
	v_mfma_f32_16x16x32_bf16 v[6:9], v[194:197], v[184:187], v[6:9]
	v_mfma_f32_16x16x32_bf16 v[2:5], v[202:205], v[184:187], v[2:5]
	v_mfma_f32_16x16x32_bf16 v[54:57], v[198:201], v[164:167], v[54:57]
	v_mfma_f32_16x16x32_bf16 v[50:53], v[206:209], v[164:167], v[50:53]
	v_mfma_f32_16x16x32_bf16 v[38:41], v[198:201], v[172:175], v[38:41]
	v_mfma_f32_16x16x32_bf16 v[34:37], v[206:209], v[172:175], v[34:37]
	v_mfma_f32_16x16x32_bf16 v[22:25], v[198:201], v[180:183], v[22:25]
	v_mfma_f32_16x16x32_bf16 v[18:21], v[206:209], v[180:183], v[18:21]
	v_mfma_f32_16x16x32_bf16 v[6:9], v[198:201], v[190:193], v[6:9]
	v_mfma_f32_16x16x32_bf16 v[2:5], v[206:209], v[190:193], v[2:5]
	s_add_i32 s86, 0, 0x18000
	v_add_u32_e32 v0, s86, v150
	s_barrier
	ds_read_b128 v[142:145], v0
	ds_read_b128 v[146:149], v0 offset:1024
	ds_read_b128 v[152:155], v0 offset:2048
	ds_read_b128 v[156:159], v0 offset:3072
	s_add_u32 s14, s14, 0x40000
	s_addc_u32 s15, s15, 0
	s_mov_b32 m0, s28
	v_lshl_add_u64 v[194:195], s[14:15], 0, v[136:137]
	ds_read_b128 v[160:163], v151 offset:32768
	ds_read_b128 v[164:167], v151 offset:33792
	ds_read_b128 v[168:171], v151 offset:34816
	ds_read_b128 v[172:175], v151 offset:35840
	ds_read_b128 v[176:179], v151 offset:36864
	ds_read_b128 v[180:183], v151 offset:37888
	ds_read_b128 v[184:187], v151 offset:38912
	ds_read_b128 v[190:193], v151 offset:39936
	global_load_lds_dwordx4 v[194:195], off
	s_mov_b32 m0, s29
	v_lshl_add_u64 v[194:195], s[14:15], 0, v[132:133]
	global_load_lds_dwordx4 v[194:195], off
	s_waitcnt lgkmcnt(8)
	s_barrier
	s_waitcnt lgkmcnt(0)
	v_mfma_f32_16x16x32_bf16 v[126:129], v[142:145], v[160:163], v[126:129]
	v_mfma_f32_16x16x32_bf16 v[122:125], v[152:155], v[160:163], v[122:125]
	v_mfma_f32_16x16x32_bf16 v[110:113], v[142:145], v[168:171], v[110:113]
	v_mfma_f32_16x16x32_bf16 v[106:109], v[152:155], v[168:171], v[106:109]
	v_mfma_f32_16x16x32_bf16 v[94:97], v[142:145], v[176:179], v[94:97]
	v_mfma_f32_16x16x32_bf16 v[90:93], v[152:155], v[176:179], v[90:93]
	v_mfma_f32_16x16x32_bf16 v[78:81], v[142:145], v[184:187], v[78:81]
	v_mfma_f32_16x16x32_bf16 v[74:77], v[152:155], v[184:187], v[74:77]
	v_mfma_f32_16x16x32_bf16 v[126:129], v[146:149], v[164:167], v[126:129]
	v_mfma_f32_16x16x32_bf16 v[122:125], v[156:159], v[164:167], v[122:125]
	v_mfma_f32_16x16x32_bf16 v[110:113], v[146:149], v[172:175], v[110:113]
	v_mfma_f32_16x16x32_bf16 v[106:109], v[156:159], v[172:175], v[106:109]
	v_mfma_f32_16x16x32_bf16 v[94:97], v[146:149], v[180:183], v[94:97]
	v_mfma_f32_16x16x32_bf16 v[90:93], v[156:159], v[180:183], v[90:93]
	v_mfma_f32_16x16x32_bf16 v[78:81], v[146:149], v[190:193], v[78:81]
	v_mfma_f32_16x16x32_bf16 v[74:77], v[156:159], v[190:193], v[74:77]
	s_barrier
	s_add_i32 s14, 0, 0x1c000
	s_add_i32 s15, s86, s22
	v_add_u32_e32 v0, s14, v150
	v_lshl_add_u64 v[210:211], v[210:211], 0, s[40:41]
	s_mov_b32 m0, s15
	ds_read_b128 v[194:197], v0
	ds_read_b128 v[198:201], v0 offset:1024
	ds_read_b128 v[202:205], v0 offset:2048
	ds_read_b128 v[206:209], v0 offset:3072
	global_load_lds_dwordx4 v[210:211], off
	s_add_i32 m0, s15, 0x2000
	v_lshl_add_u64 v[210:211], v[212:213], 0, s[40:41]
	global_load_lds_dwordx4 v[210:211], off
	s_barrier
	s_waitcnt lgkmcnt(0)
	v_mfma_f32_16x16x32_bf16 v[118:121], v[194:197], v[160:163], v[118:121]
	v_mfma_f32_16x16x32_bf16 v[114:117], v[202:205], v[160:163], v[114:117]
	v_mfma_f32_16x16x32_bf16 v[102:105], v[194:197], v[168:171], v[102:105]
	v_mfma_f32_16x16x32_bf16 v[98:101], v[202:205], v[168:171], v[98:101]
	v_mfma_f32_16x16x32_bf16 v[86:89], v[194:197], v[176:179], v[86:89]
	v_mfma_f32_16x16x32_bf16 v[82:85], v[202:205], v[176:179], v[82:85]
	v_mfma_f32_16x16x32_bf16 v[70:73], v[194:197], v[184:187], v[70:73]
	v_mfma_f32_16x16x32_bf16 v[66:69], v[202:205], v[184:187], v[66:69]
	v_mfma_f32_16x16x32_bf16 v[118:121], v[198:201], v[164:167], v[118:121]
	v_mfma_f32_16x16x32_bf16 v[114:117], v[206:209], v[164:167], v[114:117]
	v_mfma_f32_16x16x32_bf16 v[102:105], v[198:201], v[172:175], v[102:105]
	v_mfma_f32_16x16x32_bf16 v[98:101], v[206:209], v[172:175], v[98:101]
	v_mfma_f32_16x16x32_bf16 v[86:89], v[198:201], v[180:183], v[86:89]
	v_mfma_f32_16x16x32_bf16 v[82:85], v[206:209], v[180:183], v[82:85]
	v_mfma_f32_16x16x32_bf16 v[70:73], v[198:201], v[190:193], v[70:73]
	v_mfma_f32_16x16x32_bf16 v[66:69], v[206:209], v[190:193], v[66:69]
	s_mov_b32 m0, s38
	v_lshl_add_u64 v[210:211], v[214:215], 0, s[40:41]
	s_barrier
	ds_read_b128 v[160:163], v151 offset:49152
	ds_read_b128 v[164:167], v151 offset:50176
	ds_read_b128 v[168:171], v151 offset:51200
	ds_read_b128 v[172:175], v151 offset:52224
	ds_read_b128 v[176:179], v151 offset:53248
	ds_read_b128 v[180:183], v151 offset:54272
	ds_read_b128 v[184:187], v151 offset:55296
	ds_read_b128 v[190:193], v151 offset:56320
	global_load_lds_dwordx4 v[210:211], off
	s_mov_b32 m0, s39
	v_lshl_add_u64 v[210:211], v[216:217], 0, s[40:41]
	global_load_lds_dwordx4 v[210:211], off
	s_barrier
	s_waitcnt lgkmcnt(0)
	v_mfma_f32_16x16x32_bf16 v[62:65], v[142:145], v[160:163], v[62:65]
	v_mfma_f32_16x16x32_bf16 v[58:61], v[152:155], v[160:163], v[58:61]
	v_mfma_f32_16x16x32_bf16 v[46:49], v[142:145], v[168:171], v[46:49]
	v_mfma_f32_16x16x32_bf16 v[42:45], v[152:155], v[168:171], v[42:45]
	v_mfma_f32_16x16x32_bf16 v[30:33], v[142:145], v[176:179], v[30:33]
	v_mfma_f32_16x16x32_bf16 v[26:29], v[152:155], v[176:179], v[26:29]
	v_mfma_f32_16x16x32_bf16 v[14:17], v[142:145], v[184:187], v[14:17]
	v_mfma_f32_16x16x32_bf16 v[10:13], v[152:155], v[184:187], v[10:13]
	v_mfma_f32_16x16x32_bf16 v[62:65], v[146:149], v[164:167], v[62:65]
	v_mfma_f32_16x16x32_bf16 v[58:61], v[156:159], v[164:167], v[58:61]
	v_mfma_f32_16x16x32_bf16 v[46:49], v[146:149], v[172:175], v[46:49]
	v_mfma_f32_16x16x32_bf16 v[42:45], v[156:159], v[172:175], v[42:45]
	v_mfma_f32_16x16x32_bf16 v[30:33], v[146:149], v[180:183], v[30:33]
	v_mfma_f32_16x16x32_bf16 v[26:29], v[156:159], v[180:183], v[26:29]
	v_mfma_f32_16x16x32_bf16 v[14:17], v[146:149], v[190:193], v[14:17]
	v_mfma_f32_16x16x32_bf16 v[10:13], v[156:159], v[190:193], v[10:13]
	s_barrier
	s_add_u32 s12, s12, 0x40080
	s_addc_u32 s13, s13, 0
	s_add_i32 s14, s14, s22
	s_mov_b32 m0, s14
	v_lshl_add_u64 v[142:143], s[12:13], 0, v[134:135]
	global_load_lds_dwordx4 v[142:143], off
	s_add_i32 m0, s14, 0x2000
	v_lshl_add_u64 v[142:143], s[12:13], 0, v[130:131]
	global_load_lds_dwordx4 v[142:143], off
	s_waitcnt vmcnt(6)
	s_barrier
	v_mfma_f32_16x16x32_bf16 v[54:57], v[194:197], v[160:163], v[54:57]
	v_mfma_f32_16x16x32_bf16 v[50:53], v[202:205], v[160:163], v[50:53]
	v_mfma_f32_16x16x32_bf16 v[38:41], v[194:197], v[168:171], v[38:41]
	v_mfma_f32_16x16x32_bf16 v[34:37], v[202:205], v[168:171], v[34:37]
	v_mfma_f32_16x16x32_bf16 v[22:25], v[194:197], v[176:179], v[22:25]
	v_mfma_f32_16x16x32_bf16 v[18:21], v[202:205], v[176:179], v[18:21]
	v_mfma_f32_16x16x32_bf16 v[6:9], v[194:197], v[184:187], v[6:9]
	v_mfma_f32_16x16x32_bf16 v[2:5], v[202:205], v[184:187], v[2:5]
	v_mfma_f32_16x16x32_bf16 v[54:57], v[198:201], v[164:167], v[54:57]
	v_mfma_f32_16x16x32_bf16 v[50:53], v[206:209], v[164:167], v[50:53]
	v_mfma_f32_16x16x32_bf16 v[38:41], v[198:201], v[172:175], v[38:41]
	v_mfma_f32_16x16x32_bf16 v[34:37], v[206:209], v[172:175], v[34:37]
	v_mfma_f32_16x16x32_bf16 v[22:25], v[198:201], v[180:183], v[22:25]
	v_mfma_f32_16x16x32_bf16 v[18:21], v[206:209], v[180:183], v[18:21]
	v_mfma_f32_16x16x32_bf16 v[6:9], v[198:201], v[190:193], v[6:9]
	v_mfma_f32_16x16x32_bf16 v[2:5], v[206:209], v[190:193], v[2:5]
	s_add_i32 s85, s85, 2
	s_add_u32 s4, s4, 0x100
	s_addc_u32 s5, s5, 0
	s_add_u32 s78, s78, 0x100
	s_addc_u32 s79, s79, 0
	s_cmp_gt_u32 s85, 13
	s_barrier
	s_cbranch_scc0 .LBB0_267
	v_mov_b32_e32 v156, v252
	s_mov_b64 s[4:5], -1
	v_and_b32_e32 v154, 63, v156
	s_andn2_b64 vcc, exec, s[2:3]
	v_lshlrev_b32_e32 v142, 2, v154
	s_cbranch_vccnz .LBB0_270
	v_lshlrev_b32_e32 v155, 2, v154
	s_mov_b64 s[4:5], 0

.LBB0_838:
	s_add_u32 s4, s88, 0x100
	s_addc_u32 s5, s89, 0
	s_add_i32 s79, 0, 0x10000
	v_add_u32_e32 v142, s79, v212
	ds_read_b128 v[130:133], v142
	ds_read_b128 v[134:137], v142 offset:1024
	ds_read_b128 v[138:141], v142 offset:2048
	ds_read_b128 v[142:145], v142 offset:3072
	s_cmp_eq_u32 s78, 12
	s_cselect_b32 s93, s17, s5
	s_cselect_b32 s92, s16, s4
	s_cselect_b32 s91, s15, s75
	s_cselect_b32 s90, s23, s34
	v_lshl_add_u64 v[178:179], s[88:89], 0, v[196:197]
	s_add_i32 m0, s39, 0xc000
	ds_read_b128 v[146:149], v213
	ds_read_b128 v[150:153], v213 offset:1024
	ds_read_b128 v[154:157], v213 offset:2048
	ds_read_b128 v[158:161], v213 offset:3072
	ds_read_b128 v[162:165], v213 offset:4096
	ds_read_b128 v[166:169], v213 offset:5120
	ds_read_b128 v[170:173], v213 offset:6144
	ds_read_b128 v[174:177], v213 offset:7168
	global_load_lds_dwordx4 v[178:179], off
	s_add_i32 m0, s39, 0xe000
	v_lshl_add_u64 v[178:179], s[88:89], 0, v[198:199]
	global_load_lds_dwordx4 v[178:179], off
	s_waitcnt lgkmcnt(8)
	s_barrier
	s_waitcnt lgkmcnt(0)
	v_mfma_f32_16x16x32_bf16 v[126:129], v[130:133], v[146:149], v[126:129]
	v_mfma_f32_16x16x32_bf16 v[122:125], v[138:141], v[146:149], v[122:125]
	v_mfma_f32_16x16x32_bf16 v[110:113], v[130:133], v[154:157], v[110:113]
	v_mfma_f32_16x16x32_bf16 v[106:109], v[138:141], v[154:157], v[106:109]
	v_mfma_f32_16x16x32_bf16 v[94:97], v[130:133], v[162:165], v[94:97]
	v_mfma_f32_16x16x32_bf16 v[90:93], v[138:141], v[162:165], v[90:93]
	v_mfma_f32_16x16x32_bf16 v[78:81], v[130:133], v[170:173], v[78:81]
	v_mfma_f32_16x16x32_bf16 v[74:77], v[138:141], v[170:173], v[74:77]
	v_mfma_f32_16x16x32_bf16 v[126:129], v[134:137], v[150:153], v[126:129]
	v_mfma_f32_16x16x32_bf16 v[122:125], v[142:145], v[150:153], v[122:125]
	v_mfma_f32_16x16x32_bf16 v[110:113], v[134:137], v[158:161], v[110:113]
	v_mfma_f32_16x16x32_bf16 v[106:109], v[142:145], v[158:161], v[106:109]
	v_mfma_f32_16x16x32_bf16 v[94:97], v[134:137], v[166:169], v[94:97]
	v_mfma_f32_16x16x32_bf16 v[90:93], v[142:145], v[166:169], v[90:93]
	v_mfma_f32_16x16x32_bf16 v[78:81], v[134:137], v[174:177], v[78:81]
	v_mfma_f32_16x16x32_bf16 v[74:77], v[142:145], v[174:177], v[74:77]
	s_barrier
	s_add_i32 s87, 0, 0x14000
	v_add_u32_e32 v186, s87, v212
	s_add_i32 s79, s79, s38
	ds_read_b128 v[178:181], v186
	ds_read_b128 v[182:185], v186 offset:1024
	ds_read_b128 v[200:203], v186 offset:2048
	ds_read_b128 v[204:207], v186 offset:3072
	v_lshl_add_u64 v[186:187], s[90:91], 0, v[0:1]
	s_mov_b32 m0, s79
	v_lshl_add_u64 v[208:209], s[90:91], 0, v[194:195]
	global_load_lds_dwordx4 v[186:187], off
	s_add_i32 m0, s79, 0x2000
	s_nop 0
	global_load_lds_dwordx4 v[208:209], off
	s_barrier
	s_waitcnt lgkmcnt(0)
	v_mfma_f32_16x16x32_bf16 v[118:121], v[178:181], v[146:149], v[118:121]
	v_mfma_f32_16x16x32_bf16 v[114:117], v[200:203], v[146:149], v[114:117]
	v_mfma_f32_16x16x32_bf16 v[102:105], v[178:181], v[154:157], v[102:105]
	v_mfma_f32_16x16x32_bf16 v[98:101], v[200:203], v[154:157], v[98:101]
	v_mfma_f32_16x16x32_bf16 v[86:89], v[178:181], v[162:165], v[86:89]
	v_mfma_f32_16x16x32_bf16 v[82:85], v[200:203], v[162:165], v[82:85]
	v_mfma_f32_16x16x32_bf16 v[70:73], v[178:181], v[170:173], v[70:73]
	v_mfma_f32_16x16x32_bf16 v[66:69], v[200:203], v[170:173], v[66:69]
	v_mfma_f32_16x16x32_bf16 v[118:121], v[182:185], v[150:153], v[118:121]
	v_mfma_f32_16x16x32_bf16 v[114:117], v[204:207], v[150:153], v[114:117]
	v_mfma_f32_16x16x32_bf16 v[102:105], v[182:185], v[158:161], v[102:105]
	v_mfma_f32_16x16x32_bf16 v[98:101], v[204:207], v[158:161], v[98:101]
	v_mfma_f32_16x16x32_bf16 v[86:89], v[182:185], v[166:169], v[86:89]
	v_mfma_f32_16x16x32_bf16 v[82:85], v[204:207], v[166:169], v[82:85]
	v_mfma_f32_16x16x32_bf16 v[70:73], v[182:185], v[174:177], v[70:73]
	v_mfma_f32_16x16x32_bf16 v[66:69], v[204:207], v[174:177], v[66:69]
	s_mov_b32 m0, s39
	v_lshl_add_u64 v[210:211], s[92:93], 0, v[190:191]
	s_barrier
	ds_read_b128 v[146:149], v213 offset:16384
	ds_read_b128 v[150:153], v213 offset:17408
	ds_read_b128 v[154:157], v213 offset:18432
	ds_read_b128 v[158:161], v213 offset:19456
	ds_read_b128 v[162:165], v213 offset:20480
	ds_read_b128 v[166:169], v213 offset:21504
	ds_read_b128 v[170:173], v213 offset:22528
	ds_read_b128 v[174:177], v213 offset:23552
	global_load_lds_dwordx4 v[210:211], off
	s_mov_b32 m0, s42
	v_lshl_add_u64 v[214:215], s[92:93], 0, v[192:193]
	global_load_lds_dwordx4 v[214:215], off
	s_barrier
	s_waitcnt lgkmcnt(0)
	v_mfma_f32_16x16x32_bf16 v[62:65], v[130:133], v[146:149], v[62:65]
	v_mfma_f32_16x16x32_bf16 v[58:61], v[138:141], v[146:149], v[58:61]
	v_mfma_f32_16x16x32_bf16 v[46:49], v[130:133], v[154:157], v[46:49]
	v_mfma_f32_16x16x32_bf16 v[42:45], v[138:141], v[154:157], v[42:45]
	v_mfma_f32_16x16x32_bf16 v[30:33], v[130:133], v[162:165], v[30:33]
	v_mfma_f32_16x16x32_bf16 v[26:29], v[138:141], v[162:165], v[26:29]
	v_mfma_f32_16x16x32_bf16 v[14:17], v[130:133], v[170:173], v[14:17]
	v_mfma_f32_16x16x32_bf16 v[10:13], v[138:141], v[170:173], v[10:13]
	v_mfma_f32_16x16x32_bf16 v[62:65], v[134:137], v[150:153], v[62:65]
	v_mfma_f32_16x16x32_bf16 v[58:61], v[142:145], v[150:153], v[58:61]
	v_mfma_f32_16x16x32_bf16 v[46:49], v[134:137], v[158:161], v[46:49]
	v_mfma_f32_16x16x32_bf16 v[42:45], v[142:145], v[158:161], v[42:45]
	v_mfma_f32_16x16x32_bf16 v[30:33], v[134:137], v[166:169], v[30:33]
	v_mfma_f32_16x16x32_bf16 v[26:29], v[142:145], v[166:169], v[26:29]
	v_mfma_f32_16x16x32_bf16 v[14:17], v[134:137], v[174:177], v[14:17]
	v_mfma_f32_16x16x32_bf16 v[10:13], v[142:145], v[174:177], v[10:13]
	s_barrier
	s_add_u32 s88, s90, 0x40000
	s_addc_u32 s89, s91, 0
	s_add_i32 s79, s87, s38
	s_mov_b32 m0, s79
	v_lshl_add_u64 v[130:131], s[88:89], 0, v[0:1]
	global_load_lds_dwordx4 v[130:131], off
	s_add_i32 m0, s79, 0x2000
	v_lshl_add_u64 v[130:131], s[88:89], 0, v[194:195]
	global_load_lds_dwordx4 v[130:131], off
	s_waitcnt vmcnt(6)
	s_barrier
	v_mfma_f32_16x16x32_bf16 v[54:57], v[178:181], v[146:149], v[54:57]
	v_mfma_f32_16x16x32_bf16 v[50:53], v[200:203], v[146:149], v[50:53]
	v_mfma_f32_16x16x32_bf16 v[38:41], v[178:181], v[154:157], v[38:41]
	v_mfma_f32_16x16x32_bf16 v[34:37], v[200:203], v[154:157], v[34:37]
	v_mfma_f32_16x16x32_bf16 v[22:25], v[178:181], v[162:165], v[22:25]
	v_mfma_f32_16x16x32_bf16 v[18:21], v[200:203], v[162:165], v[18:21]
	v_mfma_f32_16x16x32_bf16 v[6:9], v[178:181], v[170:173], v[6:9]
	v_mfma_f32_16x16x32_bf16 v[2:5], v[200:203], v[170:173], v[2:5]
	v_mfma_f32_16x16x32_bf16 v[54:57], v[182:185], v[150:153], v[54:57]
	v_mfma_f32_16x16x32_bf16 v[50:53], v[204:207], v[150:153], v[50:53]
	v_mfma_f32_16x16x32_bf16 v[38:41], v[182:185], v[158:161], v[38:41]
	v_mfma_f32_16x16x32_bf16 v[34:37], v[204:207], v[158:161], v[34:37]
	v_mfma_f32_16x16x32_bf16 v[22:25], v[182:185], v[166:169], v[22:25]
	v_mfma_f32_16x16x32_bf16 v[18:21], v[204:207], v[166:169], v[18:21]
	v_mfma_f32_16x16x32_bf16 v[6:9], v[182:185], v[174:177], v[6:9]
	v_mfma_f32_16x16x32_bf16 v[2:5], v[204:207], v[174:177], v[2:5]
	s_add_i32 s79, 0, 0x18000
	v_add_u32_e32 v142, s79, v212
	s_barrier
	ds_read_b128 v[130:133], v142
	ds_read_b128 v[134:137], v142 offset:1024
	ds_read_b128 v[138:141], v142 offset:2048
	ds_read_b128 v[142:145], v142 offset:3072
	s_add_u32 s88, s92, 0xc0000
	s_addc_u32 s89, s93, 0
	s_mov_b32 m0, s43
	v_lshl_add_u64 v[178:179], s[88:89], 0, v[190:191]
	ds_read_b128 v[146:149], v213 offset:32768
	ds_read_b128 v[150:153], v213 offset:33792
	ds_read_b128 v[154:157], v213 offset:34816
	ds_read_b128 v[158:161], v213 offset:35840
	ds_read_b128 v[162:165], v213 offset:36864
	ds_read_b128 v[166:169], v213 offset:37888
	ds_read_b128 v[170:173], v213 offset:38912
	ds_read_b128 v[174:177], v213 offset:39936
	global_load_lds_dwordx4 v[178:179], off
	s_mov_b32 m0, s44
	v_lshl_add_u64 v[178:179], s[88:89], 0, v[192:193]
	global_load_lds_dwordx4 v[178:179], off
	s_waitcnt lgkmcnt(8)
	s_barrier
	s_waitcnt lgkmcnt(0)
	v_mfma_f32_16x16x32_bf16 v[126:129], v[130:133], v[146:149], v[126:129]
	v_mfma_f32_16x16x32_bf16 v[122:125], v[138:141], v[146:149], v[122:125]
	v_mfma_f32_16x16x32_bf16 v[110:113], v[130:133], v[154:157], v[110:113]
	v_mfma_f32_16x16x32_bf16 v[106:109], v[138:141], v[154:157], v[106:109]
	v_mfma_f32_16x16x32_bf16 v[94:97], v[130:133], v[162:165], v[94:97]
	v_mfma_f32_16x16x32_bf16 v[90:93], v[138:141], v[162:165], v[90:93]
	v_mfma_f32_16x16x32_bf16 v[78:81], v[130:133], v[170:173], v[78:81]
	v_mfma_f32_16x16x32_bf16 v[74:77], v[138:141], v[170:173], v[74:77]
	v_mfma_f32_16x16x32_bf16 v[126:129], v[134:137], v[150:153], v[126:129]
	v_mfma_f32_16x16x32_bf16 v[122:125], v[142:145], v[150:153], v[122:125]
	v_mfma_f32_16x16x32_bf16 v[110:113], v[134:137], v[158:161], v[110:113]
	v_mfma_f32_16x16x32_bf16 v[106:109], v[142:145], v[158:161], v[106:109]
	v_mfma_f32_16x16x32_bf16 v[94:97], v[134:137], v[166:169], v[94:97]
	v_mfma_f32_16x16x32_bf16 v[90:93], v[142:145], v[166:169], v[90:93]
	v_mfma_f32_16x16x32_bf16 v[78:81], v[134:137], v[174:177], v[78:81]
	v_mfma_f32_16x16x32_bf16 v[74:77], v[142:145], v[174:177], v[74:77]
	s_barrier
	s_add_i32 s87, 0, 0x1c000
	s_add_i32 s79, s79, s38
	v_add_u32_e32 v204, s87, v212
	v_lshl_add_u64 v[186:187], v[186:187], 0, s[40:41]
	s_mov_b32 m0, s79
	ds_read_b128 v[178:181], v204
	ds_read_b128 v[182:185], v204 offset:1024
	ds_read_b128 v[200:203], v204 offset:2048
	ds_read_b128 v[204:207], v204 offset:3072
	global_load_lds_dwordx4 v[186:187], off
	s_add_i32 m0, s79, 0x2000
	v_lshl_add_u64 v[186:187], v[208:209], 0, s[40:41]
	global_load_lds_dwordx4 v[186:187], off
	s_barrier
	s_waitcnt lgkmcnt(0)
	v_mfma_f32_16x16x32_bf16 v[118:121], v[178:181], v[146:149], v[118:121]
	v_mfma_f32_16x16x32_bf16 v[114:117], v[200:203], v[146:149], v[114:117]
	v_mfma_f32_16x16x32_bf16 v[102:105], v[178:181], v[154:157], v[102:105]
	v_mfma_f32_16x16x32_bf16 v[98:101], v[200:203], v[154:157], v[98:101]
	v_mfma_f32_16x16x32_bf16 v[86:89], v[178:181], v[162:165], v[86:89]
	v_mfma_f32_16x16x32_bf16 v[82:85], v[200:203], v[162:165], v[82:85]
	v_mfma_f32_16x16x32_bf16 v[70:73], v[178:181], v[170:173], v[70:73]
	v_mfma_f32_16x16x32_bf16 v[66:69], v[200:203], v[170:173], v[66:69]
	v_mfma_f32_16x16x32_bf16 v[118:121], v[182:185], v[150:153], v[118:121]
	v_mfma_f32_16x16x32_bf16 v[114:117], v[204:207], v[150:153], v[114:117]
	v_mfma_f32_16x16x32_bf16 v[102:105], v[182:185], v[158:161], v[102:105]
	v_mfma_f32_16x16x32_bf16 v[98:101], v[204:207], v[158:161], v[98:101]
	v_mfma_f32_16x16x32_bf16 v[86:89], v[182:185], v[166:169], v[86:89]
	v_mfma_f32_16x16x32_bf16 v[82:85], v[204:207], v[166:169], v[82:85]
	v_mfma_f32_16x16x32_bf16 v[70:73], v[182:185], v[174:177], v[70:73]
	v_mfma_f32_16x16x32_bf16 v[66:69], v[204:207], v[174:177], v[66:69]
	s_mov_b32 m0, s60
	v_lshl_add_u64 v[186:187], v[210:211], 0, s[40:41]
	s_barrier
	ds_read_b128 v[146:149], v213 offset:49152
	ds_read_b128 v[150:153], v213 offset:50176
	ds_read_b128 v[154:157], v213 offset:51200
	ds_read_b128 v[158:161], v213 offset:52224
	ds_read_b128 v[162:165], v213 offset:53248
	ds_read_b128 v[166:169], v213 offset:54272
	ds_read_b128 v[170:173], v213 offset:55296
	ds_read_b128 v[174:177], v213 offset:56320
	global_load_lds_dwordx4 v[186:187], off
	s_mov_b32 m0, s61
	v_lshl_add_u64 v[186:187], v[214:215], 0, s[40:41]
	global_load_lds_dwordx4 v[186:187], off
	s_barrier
	s_waitcnt lgkmcnt(0)
	v_mfma_f32_16x16x32_bf16 v[62:65], v[130:133], v[146:149], v[62:65]
	v_mfma_f32_16x16x32_bf16 v[58:61], v[138:141], v[146:149], v[58:61]
	v_mfma_f32_16x16x32_bf16 v[46:49], v[130:133], v[154:157], v[46:49]
	v_mfma_f32_16x16x32_bf16 v[42:45], v[138:141], v[154:157], v[42:45]
	v_mfma_f32_16x16x32_bf16 v[30:33], v[130:133], v[162:165], v[30:33]
	v_mfma_f32_16x16x32_bf16 v[26:29], v[138:141], v[162:165], v[26:29]
	v_mfma_f32_16x16x32_bf16 v[14:17], v[130:133], v[170:173], v[14:17]
	v_mfma_f32_16x16x32_bf16 v[10:13], v[138:141], v[170:173], v[10:13]
	v_mfma_f32_16x16x32_bf16 v[62:65], v[134:137], v[150:153], v[62:65]
	v_mfma_f32_16x16x32_bf16 v[58:61], v[142:145], v[150:153], v[58:61]
	v_mfma_f32_16x16x32_bf16 v[46:49], v[134:137], v[158:161], v[46:49]
	v_mfma_f32_16x16x32_bf16 v[42:45], v[142:145], v[158:161], v[42:45]
	v_mfma_f32_16x16x32_bf16 v[30:33], v[134:137], v[166:169], v[30:33]
	v_mfma_f32_16x16x32_bf16 v[26:29], v[142:145], v[166:169], v[26:29]
	v_mfma_f32_16x16x32_bf16 v[14:17], v[134:137], v[174:177], v[14:17]
	v_mfma_f32_16x16x32_bf16 v[10:13], v[142:145], v[174:177], v[10:13]
	s_barrier
	s_add_u32 s88, s90, 0x40080
	s_addc_u32 s89, s91, 0
	s_add_i32 s79, s87, s38
	s_mov_b32 m0, s79
	v_lshl_add_u64 v[130:131], s[88:89], 0, v[0:1]
	global_load_lds_dwordx4 v[130:131], off
	s_add_i32 m0, s79, 0x2000
	v_lshl_add_u64 v[130:131], s[88:89], 0, v[194:195]
	global_load_lds_dwordx4 v[130:131], off
	s_waitcnt vmcnt(6)
	s_barrier
	v_mfma_f32_16x16x32_bf16 v[54:57], v[178:181], v[146:149], v[54:57]
	v_mfma_f32_16x16x32_bf16 v[50:53], v[200:203], v[146:149], v[50:53]
	v_mfma_f32_16x16x32_bf16 v[38:41], v[178:181], v[154:157], v[38:41]
	v_mfma_f32_16x16x32_bf16 v[34:37], v[200:203], v[154:157], v[34:37]
	v_mfma_f32_16x16x32_bf16 v[22:25], v[178:181], v[162:165], v[22:25]
	v_mfma_f32_16x16x32_bf16 v[18:21], v[200:203], v[162:165], v[18:21]
	v_mfma_f32_16x16x32_bf16 v[6:9], v[178:181], v[170:173], v[6:9]
	v_mfma_f32_16x16x32_bf16 v[2:5], v[200:203], v[170:173], v[2:5]
	v_mfma_f32_16x16x32_bf16 v[54:57], v[182:185], v[150:153], v[54:57]
	v_mfma_f32_16x16x32_bf16 v[50:53], v[204:207], v[150:153], v[50:53]
	v_mfma_f32_16x16x32_bf16 v[38:41], v[182:185], v[158:161], v[38:41]
	v_mfma_f32_16x16x32_bf16 v[34:37], v[204:207], v[158:161], v[34:37]
	v_mfma_f32_16x16x32_bf16 v[22:25], v[182:185], v[166:169], v[22:25]
	v_mfma_f32_16x16x32_bf16 v[18:21], v[204:207], v[166:169], v[18:21]
	v_mfma_f32_16x16x32_bf16 v[6:9], v[182:185], v[174:177], v[6:9]
	v_mfma_f32_16x16x32_bf16 v[2:5], v[204:207], v[174:177], v[2:5]
	s_add_i32 s78, s78, 2
	s_add_u32 s34, s34, 0x100
	s_addc_u32 s75, s75, 0
	s_cmp_gt_u32 s78, 13
	s_mov_b64 s[88:89], s[4:5]
	s_barrier
	s_cbranch_scc0 .LBB0_838
	s_lshl_b32 s4, s22, 8
	v_mov_b32_e32 v186, v252
	s_add_i32 s4, s4, s47
	s_nop 0
	v_and_or_b32 v202, v186, 15, s4
	s_lshl_b32 s4, s86, 8
	s_or_b32 s4, s4, s55
	v_lshrrev_b32_e32 v130, 1, v186
	v_and_or_b32 v200, v130, 24, s4
	v_ashrrev_i32_e32 v201, 31, v200
	v_ashrrev_i32_e32 v203, 31, v202
	v_lshl_add_u64 v[204:205], v[200:201], 2, s[6:7]
	v_lshlrev_b64 v[130:131], 12, v[202:203]
	v_lshl_add_u64 v[130:131], v[204:205], 0, v[130:131]
	global_load_dwordx4 v[216:219], v[130:131], off offset:16
	global_load_dwordx4 v[220:223], v[130:131], off
	global_load_dwordx4 v[178:181], v[130:131], off offset:528
	global_load_dwordx4 v[182:185], v[130:131], off offset:512
	v_or_b32_e32 v210, 16, v202
	v_ashrrev_i32_e32 v211, 31, v210
	v_lshlrev_b64 v[130:131], 12, v[210:211]
	v_or_b32_e32 v208, 32, v202
	v_lshl_add_u64 v[130:131], v[204:205], 0, v[130:131]
	v_ashrrev_i32_e32 v209, 31, v208
	global_load_dwordx4 v[170:173], v[130:131], off offset:16
	global_load_dwordx4 v[174:177], v[130:131], off
	global_load_dwordx4 v[162:165], v[130:131], off offset:528
	global_load_dwordx4 v[166:169], v[130:131], off offset:512
	v_lshlrev_b64 v[130:131], 12, v[208:209]
	v_or_b32_e32 v206, 48, v202
	v_lshl_add_u64 v[130:131], v[204:205], 0, v[130:131]
	v_ashrrev_i32_e32 v207, 31, v206
	global_load_dwordx4 v[154:157], v[130:131], off offset:16
	global_load_dwordx4 v[158:161], v[130:131], off
	global_load_dwordx4 v[138:141], v[130:131], off offset:528
	global_load_dwordx4 v[142:145], v[130:131], off offset:512
	v_lshlrev_b64 v[130:131], 12, v[206:207]
	v_lshl_add_u64 v[134:135], v[204:205], 0, v[130:131]
	global_load_dwordx4 v[146:149], v[134:135], off offset:16
	global_load_dwordx4 v[150:153], v[134:135], off
	global_load_dwordx4 v[130:133], v[134:135], off offset:528
	s_nop 0
	global_load_dwordx4 v[134:137], v[134:135], off offset:512
	v_and_b32_e32 v186, 63, v186
	v_lshlrev_b32_e32 v187, 2, v186
	v_xor_b32_e32 v215, 64, v187
	v_xor_b32_e32 v214, 0x80, v187
	v_cmp_gt_u32_e32 vcc, 16, v186
	v_lshlrev_b64 v[186:187], 10, v[202:203]
	v_lshl_add_u64 v[186:187], v[186:187], 0, v[200:201]
	s_lshl_b32 s4, s86, 2
	s_ashr_i32 s5, s4, 31
	s_waitcnt vmcnt(0)
	v_pk_add_f32 v[124:125], v[124:125], v[218:219]
	v_pk_add_f32 v[128:129], v[128:129], v[222:223]
	v_pk_add_f32 v[126:127], v[126:127], v[220:221]
	v_pk_mul_f32 v[218:219], v[128:129], v[128:129]
	v_pk_mul_f32 v[220:221], v[126:127], v[126:127]
	v_pk_add_f32 v[122:123], v[122:123], v[216:217]
	v_lshl_add_u64 v[216:217], v[186:187], 2, s[12:13]
	v_add_f32_e32 v220, v220, v221
	v_add_f32_e32 v218, v218, v219
	global_store_dwordx4 v[216:217], v[126:129], off
	global_store_dwordx4 v[216:217], v[122:125], off offset:16
	v_add_f32_e32 v222, v220, v218
	v_pk_mul_f32 v[220:221], v[122:123], v[122:123]
	v_cvt_pk_bf16_f32 v126, v126, v127
	v_cvt_pk_bf16_f32 v127, v128, v129
	v_cvt_pk_bf16_f32 v128, v122, v123
	v_cvt_pk_bf16_f32 v129, v124, v125
	v_lshl_add_u64 v[122:123], v[186:187], 1, s[8:9]
	v_pk_add_f32 v[120:121], v[120:121], v[184:185]
	v_pk_add_f32 v[118:119], v[118:119], v[182:183]
	v_pk_mul_f32 v[218:219], v[124:125], v[124:125]
	global_store_dwordx4 v[122:123], v[126:129], off
	v_pk_mul_f32 v[124:125], v[120:121], v[120:121]
	v_pk_add_f32 v[116:117], v[116:117], v[180:181]
	v_pk_mul_f32 v[126:127], v[118:119], v[118:119]
	v_pk_add_f32 v[114:115], v[114:115], v[178:179]
	v_add_f32_e32 v126, v126, v127
	v_add_f32_e32 v124, v124, v125
	v_add_f32_e32 v128, v126, v124
	v_pk_mul_f32 v[124:125], v[116:117], v[116:117]
	v_pk_mul_f32 v[126:127], v[114:115], v[114:115]
	v_add_f32_e32 v220, v220, v221
	v_add_f32_e32 v218, v218, v219
	v_add_f32_e32 v126, v126, v127
	v_add_f32_e32 v124, v124, v125
	v_add_f32_e32 v218, v220, v218
	v_add_f32_e32 v124, v126, v124
	v_add_f32_e32 v218, v222, v218
	v_add_f32_e32 v124, v128, v124
	v_add_f32_e32 v124, v218, v124
	global_store_dwordx4 v[216:217], v[118:121], off offset:512
	global_store_dwordx4 v[216:217], v[114:117], off offset:528
	s_nop 0
	v_cvt_pk_bf16_f32 v118, v118, v119
	v_cvt_pk_bf16_f32 v119, v120, v121
	v_cvt_pk_bf16_f32 v120, v114, v115
	ds_bpermute_b32 v114, v215, v124
	v_cvt_pk_bf16_f32 v121, v116, v117
	global_store_dwordx4 v[122:123], v[118:121], off offset:256
	s_waitcnt lgkmcnt(0)
	v_add_f32_e32 v114, v124, v114
	ds_bpermute_b32 v115, v214, v114
	s_and_saveexec_b64 s[22:23], vcc
	s_cbranch_execz .LBB0_841
	v_lshlrev_b64 v[116:117], 6, v[202:203]
	v_lshl_add_u64 v[116:117], s[10:11], 0, v[116:117]
	v_lshl_add_u64 v[116:117], s[4:5], 2, v[116:117]
	s_lshl_b32 s34, s45, 2
	v_lshl_add_u64 v[116:117], v[116:117], 0, s[34:35]
	s_waitcnt lgkmcnt(0)
	v_add_f32_e32 v114, v114, v115
	global_store_dword v[116:117], v114, off

.LBB0_919:
	s_add_u32 s88, s6, 0x100
	s_addc_u32 s89, s7, 0
	s_add_i32 vcc_lo, 0, 0x10000
	v_add_u32_e32 v0, vcc_lo, v254
	ds_read_b128 v[130:133], v0
	ds_read_b128 v[134:137], v0 offset:1024
	ds_read_b128 v[138:141], v0 offset:2048
	ds_read_b128 v[142:145], v0 offset:3072
	s_cmp_eq_u32 s45, 12
	s_cselect_b32 s93, s17, s89
	s_cselect_b32 s92, s22, s88
	s_cselect_b32 s91, s15, s29
	s_cselect_b32 s90, s23, s28
	v_lshl_add_u64 v[154:155], s[6:7], 0, v[164:165]
	s_add_i32 m0, s43, 0xc000
	ds_read_b128 v[146:149], v253
	ds_read_b128 v[150:153], v253 offset:1024
	ds_read_b128 v[168:171], v253 offset:2048
	ds_read_b128 v[172:175], v253 offset:3072
	ds_read_b128 v[176:179], v253 offset:4096
	ds_read_b128 v[180:183], v253 offset:5120
	ds_read_b128 v[184:187], v253 offset:6144
	ds_read_b128 v[190:193], v253 offset:7168
	global_load_lds_dwordx4 v[154:155], off
	s_add_i32 m0, s43, 0xe000
	v_lshl_add_u64 v[154:155], s[6:7], 0, v[166:167]
	global_load_lds_dwordx4 v[154:155], off
	s_waitcnt lgkmcnt(8)
	s_barrier
	s_waitcnt lgkmcnt(0)
	v_mfma_f32_16x16x32_bf16 v[126:129], v[130:133], v[146:149], v[126:129]
	v_mfma_f32_16x16x32_bf16 v[70:73], v[138:141], v[146:149], v[70:73]
	v_mfma_f32_16x16x32_bf16 v[122:125], v[130:133], v[168:171], v[122:125]
	v_mfma_f32_16x16x32_bf16 v[74:77], v[138:141], v[168:171], v[74:77]
	v_mfma_f32_16x16x32_bf16 v[114:117], v[130:133], v[176:179], v[114:117]
	v_mfma_f32_16x16x32_bf16 v[66:69], v[138:141], v[176:179], v[66:69]
	v_mfma_f32_16x16x32_bf16 v[110:113], v[130:133], v[184:187], v[110:113]
	v_mfma_f32_16x16x32_bf16 v[78:81], v[138:141], v[184:187], v[78:81]
	v_mfma_f32_16x16x32_bf16 v[126:129], v[134:137], v[150:153], v[126:129]
	v_mfma_f32_16x16x32_bf16 v[70:73], v[142:145], v[150:153], v[70:73]
	v_mfma_f32_16x16x32_bf16 v[122:125], v[134:137], v[172:175], v[122:125]
	v_mfma_f32_16x16x32_bf16 v[74:77], v[142:145], v[172:175], v[74:77]
	v_mfma_f32_16x16x32_bf16 v[114:117], v[134:137], v[180:183], v[114:117]
	v_mfma_f32_16x16x32_bf16 v[66:69], v[142:145], v[180:183], v[66:69]
	v_mfma_f32_16x16x32_bf16 v[110:113], v[134:137], v[190:193], v[110:113]
	v_mfma_f32_16x16x32_bf16 v[78:81], v[142:145], v[190:193], v[78:81]
	s_barrier
	s_add_i32 vcc_hi, 0, 0x14000
	s_add_i32 s6, vcc_lo, s39
	v_add_u32_e32 v0, vcc_hi, v254
	v_lshl_add_u64 v[154:155], s[90:91], 0, v[160:161]
	s_mov_b32 m0, s6
	ds_read_b128 v[194:197], v0
	ds_read_b128 v[198:201], v0 offset:1024
	ds_read_b128 v[202:205], v0 offset:2048
	ds_read_b128 v[206:209], v0 offset:3072
	global_load_lds_dwordx4 v[154:155], off
	s_add_i32 m0, s6, 0x2000
	v_lshl_add_u64 v[210:211], s[90:91], 0, v[156:157]
	global_load_lds_dwordx4 v[210:211], off
	s_barrier
	s_waitcnt lgkmcnt(0)
	v_mfma_f32_16x16x32_bf16 v[118:121], v[194:197], v[146:149], v[118:121]
	v_mfma_f32_16x16x32_bf16 v[94:97], v[202:205], v[146:149], v[94:97]
	v_mfma_f32_16x16x32_bf16 v[106:109], v[194:197], v[168:171], v[106:109]
	v_mfma_f32_16x16x32_bf16 v[90:93], v[202:205], v[168:171], v[90:93]
	v_mfma_f32_16x16x32_bf16 v[102:105], v[194:197], v[176:179], v[102:105]
	v_mfma_f32_16x16x32_bf16 v[82:85], v[202:205], v[176:179], v[82:85]
	v_mfma_f32_16x16x32_bf16 v[98:101], v[194:197], v[184:187], v[98:101]
	v_mfma_f32_16x16x32_bf16 v[86:89], v[202:205], v[184:187], v[86:89]
	v_mfma_f32_16x16x32_bf16 v[118:121], v[198:201], v[150:153], v[118:121]
	v_mfma_f32_16x16x32_bf16 v[94:97], v[206:209], v[150:153], v[94:97]
	v_mfma_f32_16x16x32_bf16 v[106:109], v[198:201], v[172:175], v[106:109]
	v_mfma_f32_16x16x32_bf16 v[90:93], v[206:209], v[172:175], v[90:93]
	v_mfma_f32_16x16x32_bf16 v[102:105], v[198:201], v[180:183], v[102:105]
	v_mfma_f32_16x16x32_bf16 v[82:85], v[206:209], v[180:183], v[82:85]
	v_mfma_f32_16x16x32_bf16 v[98:101], v[198:201], v[190:193], v[98:101]
	v_mfma_f32_16x16x32_bf16 v[86:89], v[206:209], v[190:193], v[86:89]
	s_mov_b32 m0, s43
	v_lshl_add_u64 v[212:213], s[92:93], 0, v[162:163]
	s_barrier
	ds_read_b128 v[146:149], v253 offset:16384
	ds_read_b128 v[150:153], v253 offset:17408
	ds_read_b128 v[168:171], v253 offset:18432
	ds_read_b128 v[172:175], v253 offset:19456
	ds_read_b128 v[176:179], v253 offset:20480
	ds_read_b128 v[180:183], v253 offset:21504
	ds_read_b128 v[184:187], v253 offset:22528
	ds_read_b128 v[190:193], v253 offset:23552
	global_load_lds_dwordx4 v[212:213], off
	s_mov_b32 m0, s60
	v_lshl_add_u64 v[214:215], s[92:93], 0, v[158:159]
	global_load_lds_dwordx4 v[214:215], off
	s_barrier
	s_waitcnt lgkmcnt(0)
	v_mfma_f32_16x16x32_bf16 v[62:65], v[130:133], v[146:149], v[62:65]
	v_mfma_f32_16x16x32_bf16 v[10:13], v[138:141], v[146:149], v[10:13]
	v_mfma_f32_16x16x32_bf16 v[58:61], v[130:133], v[168:171], v[58:61]
	v_mfma_f32_16x16x32_bf16 v[14:17], v[138:141], v[168:171], v[14:17]
	v_mfma_f32_16x16x32_bf16 v[54:57], v[130:133], v[176:179], v[54:57]
	v_mfma_f32_16x16x32_bf16 v[6:9], v[138:141], v[176:179], v[6:9]
	v_mfma_f32_16x16x32_bf16 v[42:45], v[130:133], v[184:187], v[42:45]
	v_mfma_f32_16x16x32_bf16 v[2:5], v[138:141], v[184:187], v[2:5]
	v_mfma_f32_16x16x32_bf16 v[62:65], v[134:137], v[150:153], v[62:65]
	v_mfma_f32_16x16x32_bf16 v[10:13], v[142:145], v[150:153], v[10:13]
	v_mfma_f32_16x16x32_bf16 v[58:61], v[134:137], v[172:175], v[58:61]
	v_mfma_f32_16x16x32_bf16 v[14:17], v[142:145], v[172:175], v[14:17]
	v_mfma_f32_16x16x32_bf16 v[54:57], v[134:137], v[180:183], v[54:57]
	v_mfma_f32_16x16x32_bf16 v[6:9], v[142:145], v[180:183], v[6:9]
	v_mfma_f32_16x16x32_bf16 v[42:45], v[134:137], v[190:193], v[42:45]
	v_mfma_f32_16x16x32_bf16 v[2:5], v[142:145], v[190:193], v[2:5]
	s_barrier
	s_add_u32 s6, s90, 0x40000
	s_addc_u32 s7, s91, 0
	s_add_i32 vcc_lo, vcc_hi, s39
	s_mov_b32 m0, vcc_lo
	v_lshl_add_u64 v[130:131], s[6:7], 0, v[160:161]
	global_load_lds_dwordx4 v[130:131], off
	s_add_i32 m0, vcc_lo, 0x2000
	v_lshl_add_u64 v[130:131], s[6:7], 0, v[156:157]
	global_load_lds_dwordx4 v[130:131], off
	s_waitcnt vmcnt(6)
	s_barrier
	v_mfma_f32_16x16x32_bf16 v[50:53], v[194:197], v[146:149], v[50:53]
	v_mfma_f32_16x16x32_bf16 v[26:29], v[202:205], v[146:149], v[26:29]
	v_mfma_f32_16x16x32_bf16 v[46:49], v[194:197], v[168:171], v[46:49]
	v_mfma_f32_16x16x32_bf16 v[30:33], v[202:205], v[168:171], v[30:33]
	v_mfma_f32_16x16x32_bf16 v[38:41], v[194:197], v[176:179], v[38:41]
	v_mfma_f32_16x16x32_bf16 v[22:25], v[202:205], v[176:179], v[22:25]
	v_mfma_f32_16x16x32_bf16 v[34:37], v[194:197], v[184:187], v[34:37]
	v_mfma_f32_16x16x32_bf16 v[18:21], v[202:205], v[184:187], v[18:21]
	v_mfma_f32_16x16x32_bf16 v[50:53], v[198:201], v[150:153], v[50:53]
	v_mfma_f32_16x16x32_bf16 v[26:29], v[206:209], v[150:153], v[26:29]
	v_mfma_f32_16x16x32_bf16 v[46:49], v[198:201], v[172:175], v[46:49]
	v_mfma_f32_16x16x32_bf16 v[30:33], v[206:209], v[172:175], v[30:33]
	v_mfma_f32_16x16x32_bf16 v[38:41], v[198:201], v[180:183], v[38:41]
	v_mfma_f32_16x16x32_bf16 v[22:25], v[206:209], v[180:183], v[22:25]
	v_mfma_f32_16x16x32_bf16 v[34:37], v[198:201], v[190:193], v[34:37]
	v_mfma_f32_16x16x32_bf16 v[18:21], v[206:209], v[190:193], v[18:21]
	s_add_i32 vcc_lo, 0, 0x18000
	v_add_u32_e32 v0, vcc_lo, v254
	s_barrier
	ds_read_b128 v[130:133], v0
	ds_read_b128 v[134:137], v0 offset:1024
	ds_read_b128 v[138:141], v0 offset:2048
	ds_read_b128 v[142:145], v0 offset:3072
	s_add_u32 s6, s92, 0x40000
	s_addc_u32 s7, s93, 0
	s_mov_b32 m0, s61
	v_lshl_add_u64 v[194:195], s[6:7], 0, v[162:163]
	ds_read_b128 v[146:149], v253 offset:32768
	ds_read_b128 v[150:153], v253 offset:33792
	ds_read_b128 v[168:171], v253 offset:34816
	ds_read_b128 v[172:175], v253 offset:35840
	ds_read_b128 v[176:179], v253 offset:36864
	ds_read_b128 v[180:183], v253 offset:37888
	ds_read_b128 v[184:187], v253 offset:38912
	ds_read_b128 v[190:193], v253 offset:39936
	global_load_lds_dwordx4 v[194:195], off
	s_mov_b32 m0, s72
	v_lshl_add_u64 v[194:195], s[6:7], 0, v[158:159]
	global_load_lds_dwordx4 v[194:195], off
	s_waitcnt lgkmcnt(8)
	s_barrier
	s_waitcnt lgkmcnt(0)
	v_mfma_f32_16x16x32_bf16 v[126:129], v[130:133], v[146:149], v[126:129]
	v_mfma_f32_16x16x32_bf16 v[70:73], v[138:141], v[146:149], v[70:73]
	v_mfma_f32_16x16x32_bf16 v[122:125], v[130:133], v[168:171], v[122:125]
	v_mfma_f32_16x16x32_bf16 v[74:77], v[138:141], v[168:171], v[74:77]
	v_mfma_f32_16x16x32_bf16 v[114:117], v[130:133], v[176:179], v[114:117]
	v_mfma_f32_16x16x32_bf16 v[66:69], v[138:141], v[176:179], v[66:69]
	v_mfma_f32_16x16x32_bf16 v[110:113], v[130:133], v[184:187], v[110:113]
	v_mfma_f32_16x16x32_bf16 v[78:81], v[138:141], v[184:187], v[78:81]
	v_mfma_f32_16x16x32_bf16 v[126:129], v[134:137], v[150:153], v[126:129]
	v_mfma_f32_16x16x32_bf16 v[70:73], v[142:145], v[150:153], v[70:73]
	v_mfma_f32_16x16x32_bf16 v[122:125], v[134:137], v[172:175], v[122:125]
	v_mfma_f32_16x16x32_bf16 v[74:77], v[142:145], v[172:175], v[74:77]
	v_mfma_f32_16x16x32_bf16 v[114:117], v[134:137], v[180:183], v[114:117]
	v_mfma_f32_16x16x32_bf16 v[66:69], v[142:145], v[180:183], v[66:69]
	v_mfma_f32_16x16x32_bf16 v[110:113], v[134:137], v[190:193], v[110:113]
	v_mfma_f32_16x16x32_bf16 v[78:81], v[142:145], v[190:193], v[78:81]
	s_barrier
	s_add_i32 s92, 0, 0x1c000
	s_add_i32 s6, vcc_lo, s39
	v_add_u32_e32 v0, s92, v254
	v_lshl_add_u64 v[154:155], v[154:155], 0, s[40:41]
	s_mov_b32 m0, s6
	ds_read_b128 v[194:197], v0
	ds_read_b128 v[198:201], v0 offset:1024
	ds_read_b128 v[202:205], v0 offset:2048
	ds_read_b128 v[206:209], v0 offset:3072
	global_load_lds_dwordx4 v[154:155], off
	s_add_i32 m0, s6, 0x2000
	v_lshl_add_u64 v[154:155], v[210:211], 0, s[40:41]
	global_load_lds_dwordx4 v[154:155], off
	s_barrier
	s_waitcnt lgkmcnt(0)
	v_mfma_f32_16x16x32_bf16 v[118:121], v[194:197], v[146:149], v[118:121]
	v_mfma_f32_16x16x32_bf16 v[94:97], v[202:205], v[146:149], v[94:97]
	v_mfma_f32_16x16x32_bf16 v[106:109], v[194:197], v[168:171], v[106:109]
	v_mfma_f32_16x16x32_bf16 v[90:93], v[202:205], v[168:171], v[90:93]
	v_mfma_f32_16x16x32_bf16 v[102:105], v[194:197], v[176:179], v[102:105]
	v_mfma_f32_16x16x32_bf16 v[82:85], v[202:205], v[176:179], v[82:85]
	v_mfma_f32_16x16x32_bf16 v[98:101], v[194:197], v[184:187], v[98:101]
	v_mfma_f32_16x16x32_bf16 v[86:89], v[202:205], v[184:187], v[86:89]
	v_mfma_f32_16x16x32_bf16 v[118:121], v[198:201], v[150:153], v[118:121]
	v_mfma_f32_16x16x32_bf16 v[94:97], v[206:209], v[150:153], v[94:97]
	v_mfma_f32_16x16x32_bf16 v[106:109], v[198:201], v[172:175], v[106:109]
	v_mfma_f32_16x16x32_bf16 v[90:93], v[206:209], v[172:175], v[90:93]
	v_mfma_f32_16x16x32_bf16 v[102:105], v[198:201], v[180:183], v[102:105]
	v_mfma_f32_16x16x32_bf16 v[82:85], v[206:209], v[180:183], v[82:85]
	v_mfma_f32_16x16x32_bf16 v[98:101], v[198:201], v[190:193], v[98:101]
	v_mfma_f32_16x16x32_bf16 v[86:89], v[206:209], v[190:193], v[86:89]
	s_mov_b32 m0, s95
	v_lshl_add_u64 v[154:155], v[212:213], 0, s[40:41]
	s_barrier
	ds_read_b128 v[146:149], v253 offset:49152
	ds_read_b128 v[150:153], v253 offset:50176
	ds_read_b128 v[168:171], v253 offset:51200
	ds_read_b128 v[172:175], v253 offset:52224
	ds_read_b128 v[176:179], v253 offset:53248
	ds_read_b128 v[180:183], v253 offset:54272
	ds_read_b128 v[184:187], v253 offset:55296
	ds_read_b128 v[190:193], v253 offset:56320
	global_load_lds_dwordx4 v[154:155], off
	s_mov_b32 m0, s96
	v_lshl_add_u64 v[154:155], v[214:215], 0, s[40:41]
	global_load_lds_dwordx4 v[154:155], off
	s_barrier
	s_waitcnt lgkmcnt(0)
	v_mfma_f32_16x16x32_bf16 v[62:65], v[130:133], v[146:149], v[62:65]
	v_mfma_f32_16x16x32_bf16 v[10:13], v[138:141], v[146:149], v[10:13]
	v_mfma_f32_16x16x32_bf16 v[58:61], v[130:133], v[168:171], v[58:61]
	v_mfma_f32_16x16x32_bf16 v[14:17], v[138:141], v[168:171], v[14:17]
	v_mfma_f32_16x16x32_bf16 v[54:57], v[130:133], v[176:179], v[54:57]
	v_mfma_f32_16x16x32_bf16 v[6:9], v[138:141], v[176:179], v[6:9]
	v_mfma_f32_16x16x32_bf16 v[42:45], v[130:133], v[184:187], v[42:45]
	v_mfma_f32_16x16x32_bf16 v[2:5], v[138:141], v[184:187], v[2:5]
	v_mfma_f32_16x16x32_bf16 v[62:65], v[134:137], v[150:153], v[62:65]
	v_mfma_f32_16x16x32_bf16 v[10:13], v[142:145], v[150:153], v[10:13]
	v_mfma_f32_16x16x32_bf16 v[58:61], v[134:137], v[172:175], v[58:61]
	v_mfma_f32_16x16x32_bf16 v[14:17], v[142:145], v[172:175], v[14:17]
	v_mfma_f32_16x16x32_bf16 v[54:57], v[134:137], v[180:183], v[54:57]
	v_mfma_f32_16x16x32_bf16 v[6:9], v[142:145], v[180:183], v[6:9]
	v_mfma_f32_16x16x32_bf16 v[42:45], v[134:137], v[190:193], v[42:45]
	v_mfma_f32_16x16x32_bf16 v[2:5], v[142:145], v[190:193], v[2:5]
	s_barrier
	s_add_u32 s6, s90, 0x40080
	s_addc_u32 s7, s91, 0
	s_add_i32 s90, s92, s39
	s_mov_b32 m0, s90
	v_lshl_add_u64 v[130:131], s[6:7], 0, v[160:161]
	global_load_lds_dwordx4 v[130:131], off
	s_add_i32 m0, s90, 0x2000
	v_lshl_add_u64 v[130:131], s[6:7], 0, v[156:157]
	global_load_lds_dwordx4 v[130:131], off
	s_waitcnt vmcnt(6)
	s_barrier
	v_mfma_f32_16x16x32_bf16 v[50:53], v[194:197], v[146:149], v[50:53]
	v_mfma_f32_16x16x32_bf16 v[26:29], v[202:205], v[146:149], v[26:29]
	v_mfma_f32_16x16x32_bf16 v[46:49], v[194:197], v[168:171], v[46:49]
	v_mfma_f32_16x16x32_bf16 v[30:33], v[202:205], v[168:171], v[30:33]
	v_mfma_f32_16x16x32_bf16 v[38:41], v[194:197], v[176:179], v[38:41]
	v_mfma_f32_16x16x32_bf16 v[22:25], v[202:205], v[176:179], v[22:25]
	v_mfma_f32_16x16x32_bf16 v[34:37], v[194:197], v[184:187], v[34:37]
	v_mfma_f32_16x16x32_bf16 v[18:21], v[202:205], v[184:187], v[18:21]
	v_mfma_f32_16x16x32_bf16 v[50:53], v[198:201], v[150:153], v[50:53]
	v_mfma_f32_16x16x32_bf16 v[26:29], v[206:209], v[150:153], v[26:29]
	v_mfma_f32_16x16x32_bf16 v[46:49], v[198:201], v[172:175], v[46:49]
	v_mfma_f32_16x16x32_bf16 v[30:33], v[206:209], v[172:175], v[30:33]
	v_mfma_f32_16x16x32_bf16 v[38:41], v[198:201], v[180:183], v[38:41]
	v_mfma_f32_16x16x32_bf16 v[22:25], v[206:209], v[180:183], v[22:25]
	v_mfma_f32_16x16x32_bf16 v[34:37], v[198:201], v[190:193], v[34:37]
	v_mfma_f32_16x16x32_bf16 v[18:21], v[206:209], v[190:193], v[18:21]
	s_add_i32 s45, s45, 2
	s_add_u32 s28, s28, 0x100
	s_addc_u32 s29, s29, 0
	s_cmp_gt_u32 s45, 13
	s_mov_b64 s[6:7], s[88:89]
	s_barrier
	s_cbranch_scc0 .LBB0_919
	v_mov_b32_e32 v131, v252
	s_lshl_b32 s88, s5, 7
	v_bfe_u32 v130, v131, 4, 2
	v_and_b32_e32 v134, 15, v131
	v_lshlrev_b32_e32 v0, 4, v130
	s_ashr_i32 s89, s88, 31
	s_lshl_b32 s15, s4, 8
	v_or3_b32 v135, v0, s97, v134
	s_lshl_b64 s[4:5], s[88:89], 2
	v_lshrrev_b32_e32 v140, 1, v135
	s_add_u32 s4, s73, s4
	s_addc_u32 s5, s74, s5
	v_lshlrev_b32_e32 v0, 2, v140
	v_and_b32_e32 v144, 1, v131
	v_lshl_add_u64 v[132:133], s[4:5], 0, v[0:1]
	v_cmp_eq_u32_e32 vcc, 1, v144
	v_mov_b32_e32 v0, 0xb00
	s_movk_i32 s4, 0x5000
	v_cndmask_b32_e32 v141, 0, v0, vcc
	v_lshlrev_b32_e32 v0, 2, v141
	v_lshl_add_u64 v[132:133], v[132:133], 0, v[0:1]
	v_add_co_u32_e32 v138, vcc, s4, v132
	s_mov_b32 s4, 0xb000
	s_nop 0
	v_addc_co_u32_e32 v139, vcc, 0, v133, vcc
	global_load_dword v136, v[132:133], off
	global_load_dword v137, v[138:139], off offset:2048
	v_add_co_u32_e32 v132, vcc, s4, v132
	v_add_u32_e32 v0, s88, v141
	s_nop 0
	v_addc_co_u32_e32 v133, vcc, 0, v133, vcc
	global_load_dword v138, v[132:133], off
	v_or_b32_e32 v132, v140, v0
	v_ashrrev_i32_e32 v133, 31, v132
	v_lshl_add_u64 v[132:133], v[132:133], 2, s[12:13]
	global_load_dword v139, v[132:133], off
	v_lshl_add_u32 v0, v135, 4, s78
	v_and_b32_e32 v135, 63, v131
	v_cmp_eq_u32_e32 vcc, 0, v144
	s_waitcnt vmcnt(0)
	ds_write_b128 v0, v[136:139]
	v_or_b32_e32 v0, s97, v135
	v_lshrrev_b32_e32 v0, 1, v0
	v_and_or_b32 v131, v0, 63, s55
	v_add_u32_e32 v132, s15, v131
	v_ashrrev_i32_e32 v133, 31, v132
	v_lshlrev_b64 v[132:133], 6, v[132:133]
	v_lshl_add_u64 v[132:133], s[10:11], 0, v[132:133]
	v_lshlrev_b32_e32 v0, 5, v144
	v_lshl_add_u64 v[132:133], v[132:133], 0, v[0:1]
	global_load_dwordx4 v[136:139], v[132:133], off offset:16
	global_load_dwordx4 v[140:143], v[132:133], off
	s_waitcnt vmcnt(0)
	v_add_f32_e32 v133, v138, v139
	v_add_f32_e32 v0, v140, v141
	v_add_f32_e32 v132, v142, v143
	v_add_f32_e32 v0, v0, v132
	v_add_f32_e32 v132, v136, v137
	v_add_f32_e32 v132, v132, v133
	v_add_f32_e32 v0, v0, v132
	v_lshlrev_b32_e32 v132, 2, v135
	v_xor_b32_e32 v132, 4, v132
	ds_bpermute_b32 v132, v132, v0
	s_and_saveexec_b64 s[4:5], vcc
	s_cbranch_execz .LBB0_922
	s_waitcnt lgkmcnt(0)
	v_add_f32_e32 v0, v0, v132
	v_mov_b32_e32 v132, 0x358637bd
	v_fmamk_f32 v0, v0, 0x3a800000, v132
	s_mov_b32 s6, 0x800000
	v_mul_f32_e32 v132, 0x4b800000, v0
	v_cmp_gt_f32_e32 vcc, s6, v0
	v_lshl_add_u32 v131, v131, 2, 0
	v_add_u32_e32 v131, 0x20000, v131
	v_cndmask_b32_e32 v0, v0, v132, vcc
	v_rsq_f32_e32 v0, v0
	s_nop 0
	v_mul_f32_e32 v132, 0x45800000, v0
	v_cndmask_b32_e32 v0, v0, v132, vcc
	ds_write_b32 v131, v0

.LBB0_1090:
	s_add_u32 s84, s16, 0x100
	s_addc_u32 s85, s17, 0
	s_add_i32 s90, 0, 0x10000
	v_add_u32_e32 v142, s90, v212
	ds_read_b128 v[130:133], v142
	ds_read_b128 v[134:137], v142 offset:1024
	ds_read_b128 v[138:141], v142 offset:2048
	ds_read_b128 v[142:145], v142 offset:3072
	s_cmp_eq_u32 s79, 40
	s_cselect_b32 s89, s5, s85
	s_cselect_b32 s88, s4, s84
	s_cselect_b32 s87, s7, s78
	s_cselect_b32 s86, s6, s34
	v_lshl_add_u64 v[178:179], s[16:17], 0, v[196:197]
	s_add_i32 m0, s39, 0xc000
	ds_read_b128 v[146:149], v213
	ds_read_b128 v[150:153], v213 offset:1024
	ds_read_b128 v[154:157], v213 offset:2048
	ds_read_b128 v[158:161], v213 offset:3072
	ds_read_b128 v[162:165], v213 offset:4096
	ds_read_b128 v[166:169], v213 offset:5120
	ds_read_b128 v[170:173], v213 offset:6144
	ds_read_b128 v[174:177], v213 offset:7168
	global_load_lds_dwordx4 v[178:179], off
	s_add_i32 m0, s39, 0xe000
	v_lshl_add_u64 v[178:179], s[16:17], 0, v[198:199]
	global_load_lds_dwordx4 v[178:179], off
	s_waitcnt lgkmcnt(8)
	s_barrier
	s_waitcnt lgkmcnt(0)
	v_mfma_f32_16x16x32_bf16 v[126:129], v[130:133], v[146:149], v[126:129]
	v_mfma_f32_16x16x32_bf16 v[122:125], v[138:141], v[146:149], v[122:125]
	v_mfma_f32_16x16x32_bf16 v[110:113], v[130:133], v[154:157], v[110:113]
	v_mfma_f32_16x16x32_bf16 v[106:109], v[138:141], v[154:157], v[106:109]
	v_mfma_f32_16x16x32_bf16 v[94:97], v[130:133], v[162:165], v[94:97]
	v_mfma_f32_16x16x32_bf16 v[90:93], v[138:141], v[162:165], v[90:93]
	v_mfma_f32_16x16x32_bf16 v[78:81], v[130:133], v[170:173], v[78:81]
	v_mfma_f32_16x16x32_bf16 v[74:77], v[138:141], v[170:173], v[74:77]
	v_mfma_f32_16x16x32_bf16 v[126:129], v[134:137], v[150:153], v[126:129]
	v_mfma_f32_16x16x32_bf16 v[122:125], v[142:145], v[150:153], v[122:125]
	v_mfma_f32_16x16x32_bf16 v[110:113], v[134:137], v[158:161], v[110:113]
	v_mfma_f32_16x16x32_bf16 v[106:109], v[142:145], v[158:161], v[106:109]
	v_mfma_f32_16x16x32_bf16 v[94:97], v[134:137], v[166:169], v[94:97]
	v_mfma_f32_16x16x32_bf16 v[90:93], v[142:145], v[166:169], v[90:93]
	v_mfma_f32_16x16x32_bf16 v[78:81], v[134:137], v[174:177], v[78:81]
	v_mfma_f32_16x16x32_bf16 v[74:77], v[142:145], v[174:177], v[74:77]
	s_barrier
	s_add_i32 s91, 0, 0x14000
	v_add_u32_e32 v186, s91, v212
	s_add_i32 s16, s90, s38
	ds_read_b128 v[178:181], v186
	ds_read_b128 v[182:185], v186 offset:1024
	ds_read_b128 v[200:203], v186 offset:2048
	ds_read_b128 v[204:207], v186 offset:3072
	v_lshl_add_u64 v[186:187], s[86:87], 0, v[0:1]
	s_mov_b32 m0, s16
	v_lshl_add_u64 v[208:209], s[86:87], 0, v[194:195]
	global_load_lds_dwordx4 v[186:187], off
	s_add_i32 m0, s16, 0x2000
	s_nop 0
	global_load_lds_dwordx4 v[208:209], off
	s_barrier
	s_waitcnt lgkmcnt(0)
	v_mfma_f32_16x16x32_bf16 v[118:121], v[178:181], v[146:149], v[118:121]
	v_mfma_f32_16x16x32_bf16 v[114:117], v[200:203], v[146:149], v[114:117]
	v_mfma_f32_16x16x32_bf16 v[102:105], v[178:181], v[154:157], v[102:105]
	v_mfma_f32_16x16x32_bf16 v[98:101], v[200:203], v[154:157], v[98:101]
	v_mfma_f32_16x16x32_bf16 v[86:89], v[178:181], v[162:165], v[86:89]
	v_mfma_f32_16x16x32_bf16 v[82:85], v[200:203], v[162:165], v[82:85]
	v_mfma_f32_16x16x32_bf16 v[70:73], v[178:181], v[170:173], v[70:73]
	v_mfma_f32_16x16x32_bf16 v[66:69], v[200:203], v[170:173], v[66:69]
	v_mfma_f32_16x16x32_bf16 v[118:121], v[182:185], v[150:153], v[118:121]
	v_mfma_f32_16x16x32_bf16 v[114:117], v[204:207], v[150:153], v[114:117]
	v_mfma_f32_16x16x32_bf16 v[102:105], v[182:185], v[158:161], v[102:105]
	v_mfma_f32_16x16x32_bf16 v[98:101], v[204:207], v[158:161], v[98:101]
	v_mfma_f32_16x16x32_bf16 v[86:89], v[182:185], v[166:169], v[86:89]
	v_mfma_f32_16x16x32_bf16 v[82:85], v[204:207], v[166:169], v[82:85]
	v_mfma_f32_16x16x32_bf16 v[70:73], v[182:185], v[174:177], v[70:73]
	v_mfma_f32_16x16x32_bf16 v[66:69], v[204:207], v[174:177], v[66:69]
	s_mov_b32 m0, s39
	v_lshl_add_u64 v[210:211], s[88:89], 0, v[190:191]
	s_barrier
	ds_read_b128 v[146:149], v213 offset:16384
	ds_read_b128 v[150:153], v213 offset:17408
	ds_read_b128 v[154:157], v213 offset:18432
	ds_read_b128 v[158:161], v213 offset:19456
	ds_read_b128 v[162:165], v213 offset:20480
	ds_read_b128 v[166:169], v213 offset:21504
	ds_read_b128 v[170:173], v213 offset:22528
	ds_read_b128 v[174:177], v213 offset:23552
	global_load_lds_dwordx4 v[210:211], off
	s_mov_b32 m0, s42
	v_lshl_add_u64 v[214:215], s[88:89], 0, v[192:193]
	global_load_lds_dwordx4 v[214:215], off
	s_barrier
	s_waitcnt lgkmcnt(0)
	v_mfma_f32_16x16x32_bf16 v[62:65], v[130:133], v[146:149], v[62:65]
	v_mfma_f32_16x16x32_bf16 v[58:61], v[138:141], v[146:149], v[58:61]
	v_mfma_f32_16x16x32_bf16 v[46:49], v[130:133], v[154:157], v[46:49]
	v_mfma_f32_16x16x32_bf16 v[42:45], v[138:141], v[154:157], v[42:45]
	v_mfma_f32_16x16x32_bf16 v[30:33], v[130:133], v[162:165], v[30:33]
	v_mfma_f32_16x16x32_bf16 v[26:29], v[138:141], v[162:165], v[26:29]
	v_mfma_f32_16x16x32_bf16 v[14:17], v[130:133], v[170:173], v[14:17]
	v_mfma_f32_16x16x32_bf16 v[10:13], v[138:141], v[170:173], v[10:13]
	v_mfma_f32_16x16x32_bf16 v[62:65], v[134:137], v[150:153], v[62:65]
	v_mfma_f32_16x16x32_bf16 v[58:61], v[142:145], v[150:153], v[58:61]
	v_mfma_f32_16x16x32_bf16 v[46:49], v[134:137], v[158:161], v[46:49]
	v_mfma_f32_16x16x32_bf16 v[42:45], v[142:145], v[158:161], v[42:45]
	v_mfma_f32_16x16x32_bf16 v[30:33], v[134:137], v[166:169], v[30:33]
	v_mfma_f32_16x16x32_bf16 v[26:29], v[142:145], v[166:169], v[26:29]
	v_mfma_f32_16x16x32_bf16 v[14:17], v[134:137], v[174:177], v[14:17]
	v_mfma_f32_16x16x32_bf16 v[10:13], v[142:145], v[174:177], v[10:13]
	s_barrier
	s_add_u32 s16, s86, 0xb0000
	s_addc_u32 s17, s87, 0
	s_add_i32 s90, s91, s38
	s_mov_b32 m0, s90
	v_lshl_add_u64 v[130:131], s[16:17], 0, v[0:1]
	global_load_lds_dwordx4 v[130:131], off
	s_add_i32 m0, s90, 0x2000
	v_lshl_add_u64 v[130:131], s[16:17], 0, v[194:195]
	global_load_lds_dwordx4 v[130:131], off
	s_waitcnt vmcnt(6)
	s_barrier
	v_mfma_f32_16x16x32_bf16 v[54:57], v[178:181], v[146:149], v[54:57]
	v_mfma_f32_16x16x32_bf16 v[50:53], v[200:203], v[146:149], v[50:53]
	v_mfma_f32_16x16x32_bf16 v[38:41], v[178:181], v[154:157], v[38:41]
	v_mfma_f32_16x16x32_bf16 v[34:37], v[200:203], v[154:157], v[34:37]
	v_mfma_f32_16x16x32_bf16 v[22:25], v[178:181], v[162:165], v[22:25]
	v_mfma_f32_16x16x32_bf16 v[18:21], v[200:203], v[162:165], v[18:21]
	v_mfma_f32_16x16x32_bf16 v[6:9], v[178:181], v[170:173], v[6:9]
	v_mfma_f32_16x16x32_bf16 v[2:5], v[200:203], v[170:173], v[2:5]
	v_mfma_f32_16x16x32_bf16 v[54:57], v[182:185], v[150:153], v[54:57]
	v_mfma_f32_16x16x32_bf16 v[50:53], v[204:207], v[150:153], v[50:53]
	v_mfma_f32_16x16x32_bf16 v[38:41], v[182:185], v[158:161], v[38:41]
	v_mfma_f32_16x16x32_bf16 v[34:37], v[204:207], v[158:161], v[34:37]
	v_mfma_f32_16x16x32_bf16 v[22:25], v[182:185], v[166:169], v[22:25]
	v_mfma_f32_16x16x32_bf16 v[18:21], v[204:207], v[166:169], v[18:21]
	v_mfma_f32_16x16x32_bf16 v[6:9], v[182:185], v[174:177], v[6:9]
	v_mfma_f32_16x16x32_bf16 v[2:5], v[204:207], v[174:177], v[2:5]
	s_add_i32 s90, 0, 0x18000
	v_add_u32_e32 v142, s90, v212
	s_barrier
	ds_read_b128 v[130:133], v142
	ds_read_b128 v[134:137], v142 offset:1024
	ds_read_b128 v[138:141], v142 offset:2048
	ds_read_b128 v[142:145], v142 offset:3072
	s_add_u32 s16, s88, 0xb0000
	s_addc_u32 s17, s89, 0
	s_mov_b32 m0, s43
	v_lshl_add_u64 v[178:179], s[16:17], 0, v[190:191]
	ds_read_b128 v[146:149], v213 offset:32768
	ds_read_b128 v[150:153], v213 offset:33792
	ds_read_b128 v[154:157], v213 offset:34816
	ds_read_b128 v[158:161], v213 offset:35840
	ds_read_b128 v[162:165], v213 offset:36864
	ds_read_b128 v[166:169], v213 offset:37888
	ds_read_b128 v[170:173], v213 offset:38912
	ds_read_b128 v[174:177], v213 offset:39936
	global_load_lds_dwordx4 v[178:179], off
	s_mov_b32 m0, s44
	v_lshl_add_u64 v[178:179], s[16:17], 0, v[192:193]
	global_load_lds_dwordx4 v[178:179], off
	s_waitcnt lgkmcnt(8)
	s_barrier
	s_waitcnt lgkmcnt(0)
	v_mfma_f32_16x16x32_bf16 v[126:129], v[130:133], v[146:149], v[126:129]
	v_mfma_f32_16x16x32_bf16 v[122:125], v[138:141], v[146:149], v[122:125]
	v_mfma_f32_16x16x32_bf16 v[110:113], v[130:133], v[154:157], v[110:113]
	v_mfma_f32_16x16x32_bf16 v[106:109], v[138:141], v[154:157], v[106:109]
	v_mfma_f32_16x16x32_bf16 v[94:97], v[130:133], v[162:165], v[94:97]
	v_mfma_f32_16x16x32_bf16 v[90:93], v[138:141], v[162:165], v[90:93]
	v_mfma_f32_16x16x32_bf16 v[78:81], v[130:133], v[170:173], v[78:81]
	v_mfma_f32_16x16x32_bf16 v[74:77], v[138:141], v[170:173], v[74:77]
	v_mfma_f32_16x16x32_bf16 v[126:129], v[134:137], v[150:153], v[126:129]
	v_mfma_f32_16x16x32_bf16 v[122:125], v[142:145], v[150:153], v[122:125]
	v_mfma_f32_16x16x32_bf16 v[110:113], v[134:137], v[158:161], v[110:113]
	v_mfma_f32_16x16x32_bf16 v[106:109], v[142:145], v[158:161], v[106:109]
	v_mfma_f32_16x16x32_bf16 v[94:97], v[134:137], v[166:169], v[94:97]
	v_mfma_f32_16x16x32_bf16 v[90:93], v[142:145], v[166:169], v[90:93]
	v_mfma_f32_16x16x32_bf16 v[78:81], v[134:137], v[174:177], v[78:81]
	v_mfma_f32_16x16x32_bf16 v[74:77], v[142:145], v[174:177], v[74:77]
	s_barrier
	s_add_i32 s88, 0, 0x1c000
	s_add_i32 s16, s90, s38
	v_add_u32_e32 v204, s88, v212
	v_lshl_add_u64 v[186:187], v[186:187], 0, s[40:41]
	s_mov_b32 m0, s16
	ds_read_b128 v[178:181], v204
	ds_read_b128 v[182:185], v204 offset:1024
	ds_read_b128 v[200:203], v204 offset:2048
	ds_read_b128 v[204:207], v204 offset:3072
	global_load_lds_dwordx4 v[186:187], off
	s_add_i32 m0, s16, 0x2000
	v_lshl_add_u64 v[186:187], v[208:209], 0, s[40:41]
	global_load_lds_dwordx4 v[186:187], off
	s_barrier
	s_waitcnt lgkmcnt(0)
	v_mfma_f32_16x16x32_bf16 v[118:121], v[178:181], v[146:149], v[118:121]
	v_mfma_f32_16x16x32_bf16 v[114:117], v[200:203], v[146:149], v[114:117]
	v_mfma_f32_16x16x32_bf16 v[102:105], v[178:181], v[154:157], v[102:105]
	v_mfma_f32_16x16x32_bf16 v[98:101], v[200:203], v[154:157], v[98:101]
	v_mfma_f32_16x16x32_bf16 v[86:89], v[178:181], v[162:165], v[86:89]
	v_mfma_f32_16x16x32_bf16 v[82:85], v[200:203], v[162:165], v[82:85]
	v_mfma_f32_16x16x32_bf16 v[70:73], v[178:181], v[170:173], v[70:73]
	v_mfma_f32_16x16x32_bf16 v[66:69], v[200:203], v[170:173], v[66:69]
	v_mfma_f32_16x16x32_bf16 v[118:121], v[182:185], v[150:153], v[118:121]
	v_mfma_f32_16x16x32_bf16 v[114:117], v[204:207], v[150:153], v[114:117]
	v_mfma_f32_16x16x32_bf16 v[102:105], v[182:185], v[158:161], v[102:105]
	v_mfma_f32_16x16x32_bf16 v[98:101], v[204:207], v[158:161], v[98:101]
	v_mfma_f32_16x16x32_bf16 v[86:89], v[182:185], v[166:169], v[86:89]
	v_mfma_f32_16x16x32_bf16 v[82:85], v[204:207], v[166:169], v[82:85]
	v_mfma_f32_16x16x32_bf16 v[70:73], v[182:185], v[174:177], v[70:73]
	v_mfma_f32_16x16x32_bf16 v[66:69], v[204:207], v[174:177], v[66:69]
	s_mov_b32 m0, s60
	v_lshl_add_u64 v[186:187], v[210:211], 0, s[40:41]
	s_barrier
	ds_read_b128 v[146:149], v213 offset:49152
	ds_read_b128 v[150:153], v213 offset:50176
	ds_read_b128 v[154:157], v213 offset:51200
	ds_read_b128 v[158:161], v213 offset:52224
	ds_read_b128 v[162:165], v213 offset:53248
	ds_read_b128 v[166:169], v213 offset:54272
	ds_read_b128 v[170:173], v213 offset:55296
	ds_read_b128 v[174:177], v213 offset:56320
	global_load_lds_dwordx4 v[186:187], off
	s_mov_b32 m0, s61
	v_lshl_add_u64 v[186:187], v[214:215], 0, s[40:41]
	global_load_lds_dwordx4 v[186:187], off
	s_barrier
	s_waitcnt lgkmcnt(0)
	v_mfma_f32_16x16x32_bf16 v[62:65], v[130:133], v[146:149], v[62:65]
	v_mfma_f32_16x16x32_bf16 v[58:61], v[138:141], v[146:149], v[58:61]
	v_mfma_f32_16x16x32_bf16 v[46:49], v[130:133], v[154:157], v[46:49]
	v_mfma_f32_16x16x32_bf16 v[42:45], v[138:141], v[154:157], v[42:45]
	v_mfma_f32_16x16x32_bf16 v[30:33], v[130:133], v[162:165], v[30:33]
	v_mfma_f32_16x16x32_bf16 v[26:29], v[138:141], v[162:165], v[26:29]
	v_mfma_f32_16x16x32_bf16 v[14:17], v[130:133], v[170:173], v[14:17]
	v_mfma_f32_16x16x32_bf16 v[10:13], v[138:141], v[170:173], v[10:13]
	v_mfma_f32_16x16x32_bf16 v[62:65], v[134:137], v[150:153], v[62:65]
	v_mfma_f32_16x16x32_bf16 v[58:61], v[142:145], v[150:153], v[58:61]
	v_mfma_f32_16x16x32_bf16 v[46:49], v[134:137], v[158:161], v[46:49]
	v_mfma_f32_16x16x32_bf16 v[42:45], v[142:145], v[158:161], v[42:45]
	v_mfma_f32_16x16x32_bf16 v[30:33], v[134:137], v[166:169], v[30:33]
	v_mfma_f32_16x16x32_bf16 v[26:29], v[142:145], v[166:169], v[26:29]
	v_mfma_f32_16x16x32_bf16 v[14:17], v[134:137], v[174:177], v[14:17]
	v_mfma_f32_16x16x32_bf16 v[10:13], v[142:145], v[174:177], v[10:13]
	s_barrier
	s_add_u32 s16, s86, 0xb0080
	s_addc_u32 s17, s87, 0
	s_add_i32 s86, s88, s38
	s_mov_b32 m0, s86
	v_lshl_add_u64 v[130:131], s[16:17], 0, v[0:1]
	global_load_lds_dwordx4 v[130:131], off
	s_add_i32 m0, s86, 0x2000
	v_lshl_add_u64 v[130:131], s[16:17], 0, v[194:195]
	global_load_lds_dwordx4 v[130:131], off
	s_waitcnt vmcnt(6)
	s_barrier
	v_mfma_f32_16x16x32_bf16 v[54:57], v[178:181], v[146:149], v[54:57]
	v_mfma_f32_16x16x32_bf16 v[50:53], v[200:203], v[146:149], v[50:53]
	v_mfma_f32_16x16x32_bf16 v[38:41], v[178:181], v[154:157], v[38:41]
	v_mfma_f32_16x16x32_bf16 v[34:37], v[200:203], v[154:157], v[34:37]
	v_mfma_f32_16x16x32_bf16 v[22:25], v[178:181], v[162:165], v[22:25]
	v_mfma_f32_16x16x32_bf16 v[18:21], v[200:203], v[162:165], v[18:21]
	v_mfma_f32_16x16x32_bf16 v[6:9], v[178:181], v[170:173], v[6:9]
	v_mfma_f32_16x16x32_bf16 v[2:5], v[200:203], v[170:173], v[2:5]
	v_mfma_f32_16x16x32_bf16 v[54:57], v[182:185], v[150:153], v[54:57]
	v_mfma_f32_16x16x32_bf16 v[50:53], v[204:207], v[150:153], v[50:53]
	v_mfma_f32_16x16x32_bf16 v[38:41], v[182:185], v[158:161], v[38:41]
	v_mfma_f32_16x16x32_bf16 v[34:37], v[204:207], v[158:161], v[34:37]
	v_mfma_f32_16x16x32_bf16 v[22:25], v[182:185], v[166:169], v[22:25]
	v_mfma_f32_16x16x32_bf16 v[18:21], v[204:207], v[166:169], v[18:21]
	v_mfma_f32_16x16x32_bf16 v[6:9], v[182:185], v[174:177], v[6:9]
	v_mfma_f32_16x16x32_bf16 v[2:5], v[204:207], v[174:177], v[2:5]
	s_add_i32 s79, s79, 2
	s_add_u32 s34, s34, 0x100
	s_addc_u32 s78, s78, 0
	s_cmp_gt_u32 s79, 41
	s_mov_b64 s[16:17], s[84:85]
	s_barrier
	s_cbranch_scc0 .LBB0_1090
	s_lshl_b32 s16, s23, 8
	v_mov_b32_e32 v186, v252
	s_add_i32 s16, s16, s47
	s_nop 0
	v_and_or_b32 v202, v186, 15, s16
	s_lshl_b32 s16, s22, 8
	s_or_b32 s16, s16, s55
	v_lshrrev_b32_e32 v130, 1, v186
	v_and_or_b32 v200, v130, 24, s16
	v_ashrrev_i32_e32 v201, 31, v200
	v_ashrrev_i32_e32 v203, 31, v202
	v_lshl_add_u64 v[204:205], v[200:201], 2, s[12:13]
	v_lshlrev_b64 v[130:131], 12, v[202:203]
	v_lshl_add_u64 v[130:131], v[204:205], 0, v[130:131]
	global_load_dwordx4 v[216:219], v[130:131], off offset:16
	global_load_dwordx4 v[220:223], v[130:131], off
	global_load_dwordx4 v[178:181], v[130:131], off offset:528
	global_load_dwordx4 v[182:185], v[130:131], off offset:512
	v_or_b32_e32 v210, 16, v202
	v_ashrrev_i32_e32 v211, 31, v210
	v_lshlrev_b64 v[130:131], 12, v[210:211]
	v_or_b32_e32 v208, 32, v202
	v_lshl_add_u64 v[130:131], v[204:205], 0, v[130:131]
	v_ashrrev_i32_e32 v209, 31, v208
	global_load_dwordx4 v[170:173], v[130:131], off offset:16
	global_load_dwordx4 v[174:177], v[130:131], off
	global_load_dwordx4 v[162:165], v[130:131], off offset:528
	global_load_dwordx4 v[166:169], v[130:131], off offset:512
	v_lshlrev_b64 v[130:131], 12, v[208:209]
	v_or_b32_e32 v206, 48, v202
	v_lshl_add_u64 v[130:131], v[204:205], 0, v[130:131]
	v_ashrrev_i32_e32 v207, 31, v206
	global_load_dwordx4 v[154:157], v[130:131], off offset:16
	global_load_dwordx4 v[158:161], v[130:131], off
	global_load_dwordx4 v[138:141], v[130:131], off offset:528
	global_load_dwordx4 v[142:145], v[130:131], off offset:512
	v_lshlrev_b64 v[130:131], 12, v[206:207]
	v_lshl_add_u64 v[134:135], v[204:205], 0, v[130:131]
	global_load_dwordx4 v[146:149], v[134:135], off offset:16
	global_load_dwordx4 v[150:153], v[134:135], off
	global_load_dwordx4 v[130:133], v[134:135], off offset:528
	s_nop 0
	global_load_dwordx4 v[134:137], v[134:135], off offset:512
	v_and_b32_e32 v186, 63, v186
	v_lshlrev_b32_e32 v187, 2, v186
	v_xor_b32_e32 v215, 64, v187
	v_xor_b32_e32 v214, 0x80, v187
	v_cmp_gt_u32_e32 vcc, 16, v186
	v_lshlrev_b64 v[186:187], 10, v[202:203]
	v_lshl_add_u64 v[186:187], v[186:187], 0, v[200:201]
	s_lshl_b32 s16, s22, 2
	s_ashr_i32 s17, s16, 31
	s_waitcnt vmcnt(0)
	v_pk_add_f32 v[124:125], v[124:125], v[218:219]
	v_pk_add_f32 v[128:129], v[128:129], v[222:223]
	v_pk_add_f32 v[126:127], v[126:127], v[220:221]
	v_pk_mul_f32 v[218:219], v[128:129], v[128:129]
	v_pk_mul_f32 v[220:221], v[126:127], v[126:127]
	v_pk_add_f32 v[122:123], v[122:123], v[216:217]
	v_lshl_add_u64 v[216:217], v[186:187], 2, s[14:15]
	v_add_f32_e32 v220, v220, v221
	v_add_f32_e32 v218, v218, v219
	global_store_dwordx4 v[216:217], v[126:129], off
	global_store_dwordx4 v[216:217], v[122:125], off offset:16
	v_add_f32_e32 v222, v220, v218
	v_pk_mul_f32 v[220:221], v[122:123], v[122:123]
	v_cvt_pk_bf16_f32 v126, v126, v127
	v_cvt_pk_bf16_f32 v127, v128, v129
	v_cvt_pk_bf16_f32 v128, v122, v123
	v_cvt_pk_bf16_f32 v129, v124, v125
	v_lshl_add_u64 v[122:123], v[186:187], 1, s[80:81]
	v_pk_add_f32 v[120:121], v[120:121], v[184:185]
	v_pk_add_f32 v[118:119], v[118:119], v[182:183]
	v_pk_mul_f32 v[218:219], v[124:125], v[124:125]
	global_store_dwordx4 v[122:123], v[126:129], off
	v_pk_mul_f32 v[124:125], v[120:121], v[120:121]
	v_pk_add_f32 v[116:117], v[116:117], v[180:181]
	v_pk_mul_f32 v[126:127], v[118:119], v[118:119]
	v_pk_add_f32 v[114:115], v[114:115], v[178:179]
	v_add_f32_e32 v126, v126, v127
	v_add_f32_e32 v124, v124, v125
	v_add_f32_e32 v128, v126, v124
	v_pk_mul_f32 v[124:125], v[116:117], v[116:117]
	v_pk_mul_f32 v[126:127], v[114:115], v[114:115]
	v_add_f32_e32 v220, v220, v221
	v_add_f32_e32 v218, v218, v219
	v_add_f32_e32 v126, v126, v127
	v_add_f32_e32 v124, v124, v125
	v_add_f32_e32 v218, v220, v218
	v_add_f32_e32 v124, v126, v124
	v_add_f32_e32 v218, v222, v218
	v_add_f32_e32 v124, v128, v124
	v_add_f32_e32 v124, v218, v124
	global_store_dwordx4 v[216:217], v[118:121], off offset:512
	global_store_dwordx4 v[216:217], v[114:117], off offset:528
	s_nop 0
	v_cvt_pk_bf16_f32 v118, v118, v119
	v_cvt_pk_bf16_f32 v119, v120, v121
	v_cvt_pk_bf16_f32 v120, v114, v115
	ds_bpermute_b32 v114, v215, v124
	v_cvt_pk_bf16_f32 v121, v116, v117
	global_store_dwordx4 v[122:123], v[118:121], off offset:256
	s_waitcnt lgkmcnt(0)
	v_add_f32_e32 v114, v124, v114
	ds_bpermute_b32 v115, v214, v114
	s_and_saveexec_b64 s[22:23], vcc
	s_cbranch_execz .LBB0_1093
	v_lshlrev_b64 v[116:117], 6, v[202:203]
	v_lshl_add_u64 v[116:117], s[82:83], 0, v[116:117]
	v_lshl_add_u64 v[116:117], s[16:17], 2, v[116:117]
	s_lshl_b32 s34, s45, 2
	v_lshl_add_u64 v[116:117], v[116:117], 0, s[34:35]
	s_waitcnt lgkmcnt(0)
	v_add_f32_e32 v114, v114, v115
	global_store_dword v[116:117], v114, off

.LBB0_1209:
	s_add_u32 s87, s88, 0xfffc0080
	s_addc_u32 s90, s89, -1
	s_add_i32 s94, 0, 0x10000
	s_waitcnt lgkmcnt(0)
	v_add_u32_e32 v0, s94, v170
	ds_read_b128 v[130:133], v0
	ds_read_b128 v[134:137], v0 offset:1024
	ds_read_b128 v[138:141], v0 offset:2048
	ds_read_b128 v[142:145], v0 offset:3072
	s_cmp_eq_u32 s85, 12
	s_cselect_b32 s93, s13, s90
	s_cselect_b32 s92, s22, s87
	s_cselect_b32 s91, s7, s79
	s_cselect_b32 s90, s23, s34
	v_lshl_add_u64 v[194:195], s[88:89], 0, v[154:155]
	s_add_i32 m0, s39, 0xc000
	ds_read_b128 v[158:161], v171
	ds_read_b128 v[162:165], v171 offset:1024
	ds_read_b128 v[166:169], v171 offset:2048
	ds_read_b128 v[172:175], v171 offset:3072
	ds_read_b128 v[176:179], v171 offset:4096
	ds_read_b128 v[180:183], v171 offset:5120
	ds_read_b128 v[184:187], v171 offset:6144
	ds_read_b128 v[190:193], v171 offset:7168
	global_load_lds_dwordx4 v[194:195], off
	s_add_i32 m0, s39, 0xe000
	v_lshl_add_u64 v[194:195], s[88:89], 0, v[156:157]
	global_load_lds_dwordx4 v[194:195], off
	s_waitcnt lgkmcnt(8)
	s_barrier
	s_waitcnt lgkmcnt(0)
	v_mfma_f32_16x16x32_bf16 v[126:129], v[130:133], v[158:161], v[126:129]
	v_mfma_f32_16x16x32_bf16 v[122:125], v[138:141], v[158:161], v[122:125]
	v_mfma_f32_16x16x32_bf16 v[110:113], v[130:133], v[166:169], v[110:113]
	v_mfma_f32_16x16x32_bf16 v[106:109], v[138:141], v[166:169], v[106:109]
	v_mfma_f32_16x16x32_bf16 v[94:97], v[130:133], v[176:179], v[94:97]
	v_mfma_f32_16x16x32_bf16 v[90:93], v[138:141], v[176:179], v[90:93]
	v_mfma_f32_16x16x32_bf16 v[78:81], v[130:133], v[184:187], v[78:81]
	v_mfma_f32_16x16x32_bf16 v[74:77], v[138:141], v[184:187], v[74:77]
	v_mfma_f32_16x16x32_bf16 v[126:129], v[134:137], v[162:165], v[126:129]
	v_mfma_f32_16x16x32_bf16 v[122:125], v[142:145], v[162:165], v[122:125]
	v_mfma_f32_16x16x32_bf16 v[110:113], v[134:137], v[172:175], v[110:113]
	v_mfma_f32_16x16x32_bf16 v[106:109], v[142:145], v[172:175], v[106:109]
	v_mfma_f32_16x16x32_bf16 v[94:97], v[134:137], v[180:183], v[94:97]
	v_mfma_f32_16x16x32_bf16 v[90:93], v[142:145], v[180:183], v[90:93]
	v_mfma_f32_16x16x32_bf16 v[78:81], v[134:137], v[190:193], v[78:81]
	v_mfma_f32_16x16x32_bf16 v[74:77], v[142:145], v[190:193], v[74:77]
	s_barrier
	s_add_i32 s87, 0, 0x14000
	s_add_i32 s94, s94, s38
	v_add_u32_e32 v0, s87, v170
	v_lshl_add_u64 v[210:211], s[90:91], 0, v[148:149]
	s_mov_b32 m0, s94
	ds_read_b128 v[194:197], v0
	ds_read_b128 v[198:201], v0 offset:1024
	ds_read_b128 v[202:205], v0 offset:2048
	ds_read_b128 v[206:209], v0 offset:3072
	global_load_lds_dwordx4 v[210:211], off
	s_add_i32 m0, s94, 0x2000
	v_lshl_add_u64 v[212:213], s[90:91], 0, v[152:153]
	global_load_lds_dwordx4 v[212:213], off
	s_barrier
	s_waitcnt lgkmcnt(0)
	v_mfma_f32_16x16x32_bf16 v[118:121], v[194:197], v[158:161], v[118:121]
	v_mfma_f32_16x16x32_bf16 v[114:117], v[202:205], v[158:161], v[114:117]
	v_mfma_f32_16x16x32_bf16 v[102:105], v[194:197], v[166:169], v[102:105]
	v_mfma_f32_16x16x32_bf16 v[98:101], v[202:205], v[166:169], v[98:101]
	v_mfma_f32_16x16x32_bf16 v[86:89], v[194:197], v[176:179], v[86:89]
	v_mfma_f32_16x16x32_bf16 v[82:85], v[202:205], v[176:179], v[82:85]
	v_mfma_f32_16x16x32_bf16 v[70:73], v[194:197], v[184:187], v[70:73]
	v_mfma_f32_16x16x32_bf16 v[66:69], v[202:205], v[184:187], v[66:69]
	v_mfma_f32_16x16x32_bf16 v[118:121], v[198:201], v[162:165], v[118:121]
	v_mfma_f32_16x16x32_bf16 v[114:117], v[206:209], v[162:165], v[114:117]
	v_mfma_f32_16x16x32_bf16 v[102:105], v[198:201], v[172:175], v[102:105]
	v_mfma_f32_16x16x32_bf16 v[98:101], v[206:209], v[172:175], v[98:101]
	v_mfma_f32_16x16x32_bf16 v[86:89], v[198:201], v[180:183], v[86:89]
	v_mfma_f32_16x16x32_bf16 v[82:85], v[206:209], v[180:183], v[82:85]
	v_mfma_f32_16x16x32_bf16 v[70:73], v[198:201], v[190:193], v[70:73]
	v_mfma_f32_16x16x32_bf16 v[66:69], v[206:209], v[190:193], v[66:69]
	s_mov_b32 m0, s39
	v_lshl_add_u64 v[214:215], s[92:93], 0, v[146:147]
	s_barrier
	ds_read_b128 v[158:161], v171 offset:16384
	ds_read_b128 v[162:165], v171 offset:17408
	ds_read_b128 v[166:169], v171 offset:18432
	ds_read_b128 v[172:175], v171 offset:19456
	ds_read_b128 v[176:179], v171 offset:20480
	ds_read_b128 v[180:183], v171 offset:21504
	ds_read_b128 v[184:187], v171 offset:22528
	ds_read_b128 v[190:193], v171 offset:23552
	global_load_lds_dwordx4 v[214:215], off
	s_mov_b32 m0, s42
	v_lshl_add_u64 v[216:217], s[92:93], 0, v[150:151]
	global_load_lds_dwordx4 v[216:217], off
	s_barrier
	s_waitcnt lgkmcnt(0)
	v_mfma_f32_16x16x32_bf16 v[62:65], v[130:133], v[158:161], v[62:65]
	v_mfma_f32_16x16x32_bf16 v[58:61], v[138:141], v[158:161], v[58:61]
	v_mfma_f32_16x16x32_bf16 v[46:49], v[130:133], v[166:169], v[46:49]
	v_mfma_f32_16x16x32_bf16 v[42:45], v[138:141], v[166:169], v[42:45]
	v_mfma_f32_16x16x32_bf16 v[30:33], v[130:133], v[176:179], v[30:33]
	v_mfma_f32_16x16x32_bf16 v[26:29], v[138:141], v[176:179], v[26:29]
	v_mfma_f32_16x16x32_bf16 v[14:17], v[130:133], v[184:187], v[14:17]
	v_mfma_f32_16x16x32_bf16 v[10:13], v[138:141], v[184:187], v[10:13]
	v_mfma_f32_16x16x32_bf16 v[62:65], v[134:137], v[162:165], v[62:65]
	v_mfma_f32_16x16x32_bf16 v[58:61], v[142:145], v[162:165], v[58:61]
	v_mfma_f32_16x16x32_bf16 v[46:49], v[134:137], v[172:175], v[46:49]
	v_mfma_f32_16x16x32_bf16 v[42:45], v[142:145], v[172:175], v[42:45]
	v_mfma_f32_16x16x32_bf16 v[30:33], v[134:137], v[180:183], v[30:33]
	v_mfma_f32_16x16x32_bf16 v[26:29], v[142:145], v[180:183], v[26:29]
	v_mfma_f32_16x16x32_bf16 v[14:17], v[134:137], v[190:193], v[14:17]
	v_mfma_f32_16x16x32_bf16 v[10:13], v[142:145], v[190:193], v[10:13]
	s_barrier
	s_add_u32 s94, s90, 0x40000
	s_addc_u32 s95, s91, 0
	s_add_i32 s87, s87, s38
	s_mov_b32 m0, s87
	v_lshl_add_u64 v[130:131], s[94:95], 0, v[148:149]
	global_load_lds_dwordx4 v[130:131], off
	s_add_i32 m0, s87, 0x2000
	v_lshl_add_u64 v[130:131], s[94:95], 0, v[152:153]
	global_load_lds_dwordx4 v[130:131], off
	s_waitcnt vmcnt(6)
	s_barrier
	v_mfma_f32_16x16x32_bf16 v[54:57], v[194:197], v[158:161], v[54:57]
	v_mfma_f32_16x16x32_bf16 v[50:53], v[202:205], v[158:161], v[50:53]
	v_mfma_f32_16x16x32_bf16 v[38:41], v[194:197], v[166:169], v[38:41]
	v_mfma_f32_16x16x32_bf16 v[34:37], v[202:205], v[166:169], v[34:37]
	v_mfma_f32_16x16x32_bf16 v[22:25], v[194:197], v[176:179], v[22:25]
	v_mfma_f32_16x16x32_bf16 v[18:21], v[202:205], v[176:179], v[18:21]
	v_mfma_f32_16x16x32_bf16 v[6:9], v[194:197], v[184:187], v[6:9]
	v_mfma_f32_16x16x32_bf16 v[2:5], v[202:205], v[184:187], v[2:5]
	v_mfma_f32_16x16x32_bf16 v[54:57], v[198:201], v[162:165], v[54:57]
	v_mfma_f32_16x16x32_bf16 v[50:53], v[206:209], v[162:165], v[50:53]
	v_mfma_f32_16x16x32_bf16 v[38:41], v[198:201], v[172:175], v[38:41]
	v_mfma_f32_16x16x32_bf16 v[34:37], v[206:209], v[172:175], v[34:37]
	v_mfma_f32_16x16x32_bf16 v[22:25], v[198:201], v[180:183], v[22:25]
	v_mfma_f32_16x16x32_bf16 v[18:21], v[206:209], v[180:183], v[18:21]
	v_mfma_f32_16x16x32_bf16 v[6:9], v[198:201], v[190:193], v[6:9]
	v_mfma_f32_16x16x32_bf16 v[2:5], v[206:209], v[190:193], v[2:5]
	s_add_i32 s87, 0, 0x18000
	v_add_u32_e32 v0, s87, v170
	s_barrier
	ds_read_b128 v[130:133], v0
	ds_read_b128 v[134:137], v0 offset:1024
	ds_read_b128 v[138:141], v0 offset:2048
	ds_read_b128 v[142:145], v0 offset:3072
	s_add_u32 s92, s92, 0x40000
	s_addc_u32 s93, s93, 0
	s_mov_b32 m0, s43
	v_lshl_add_u64 v[194:195], s[92:93], 0, v[146:147]
	ds_read_b128 v[158:161], v171 offset:32768
	ds_read_b128 v[162:165], v171 offset:33792
	ds_read_b128 v[166:169], v171 offset:34816
	ds_read_b128 v[172:175], v171 offset:35840
	ds_read_b128 v[176:179], v171 offset:36864
	ds_read_b128 v[180:183], v171 offset:37888
	ds_read_b128 v[184:187], v171 offset:38912
	ds_read_b128 v[190:193], v171 offset:39936
	global_load_lds_dwordx4 v[194:195], off
	s_mov_b32 m0, s44
	v_lshl_add_u64 v[194:195], s[92:93], 0, v[150:151]
	global_load_lds_dwordx4 v[194:195], off
	s_waitcnt lgkmcnt(8)
	s_barrier
	s_waitcnt lgkmcnt(0)
	v_mfma_f32_16x16x32_bf16 v[126:129], v[130:133], v[158:161], v[126:129]
	v_mfma_f32_16x16x32_bf16 v[122:125], v[138:141], v[158:161], v[122:125]
	v_mfma_f32_16x16x32_bf16 v[110:113], v[130:133], v[166:169], v[110:113]
	v_mfma_f32_16x16x32_bf16 v[106:109], v[138:141], v[166:169], v[106:109]
	v_mfma_f32_16x16x32_bf16 v[94:97], v[130:133], v[176:179], v[94:97]
	v_mfma_f32_16x16x32_bf16 v[90:93], v[138:141], v[176:179], v[90:93]
	v_mfma_f32_16x16x32_bf16 v[78:81], v[130:133], v[184:187], v[78:81]
	v_mfma_f32_16x16x32_bf16 v[74:77], v[138:141], v[184:187], v[74:77]
	v_mfma_f32_16x16x32_bf16 v[126:129], v[134:137], v[162:165], v[126:129]
	v_mfma_f32_16x16x32_bf16 v[122:125], v[142:145], v[162:165], v[122:125]
	v_mfma_f32_16x16x32_bf16 v[110:113], v[134:137], v[172:175], v[110:113]
	v_mfma_f32_16x16x32_bf16 v[106:109], v[142:145], v[172:175], v[106:109]
	v_mfma_f32_16x16x32_bf16 v[94:97], v[134:137], v[180:183], v[94:97]
	v_mfma_f32_16x16x32_bf16 v[90:93], v[142:145], v[180:183], v[90:93]
	v_mfma_f32_16x16x32_bf16 v[78:81], v[134:137], v[190:193], v[78:81]
	v_mfma_f32_16x16x32_bf16 v[74:77], v[142:145], v[190:193], v[74:77]
	s_barrier
	s_add_i32 s92, 0, 0x1c000
	s_add_i32 s87, s87, s38
	v_add_u32_e32 v0, s92, v170
	v_lshl_add_u64 v[210:211], v[210:211], 0, s[40:41]
	s_mov_b32 m0, s87
	ds_read_b128 v[194:197], v0
	ds_read_b128 v[198:201], v0 offset:1024
	ds_read_b128 v[202:205], v0 offset:2048
	ds_read_b128 v[206:209], v0 offset:3072
	global_load_lds_dwordx4 v[210:211], off
	s_add_i32 m0, s87, 0x2000
	v_lshl_add_u64 v[210:211], v[212:213], 0, s[40:41]
	global_load_lds_dwordx4 v[210:211], off
	s_barrier
	s_waitcnt lgkmcnt(0)
	v_mfma_f32_16x16x32_bf16 v[118:121], v[194:197], v[158:161], v[118:121]
	v_mfma_f32_16x16x32_bf16 v[114:117], v[202:205], v[158:161], v[114:117]
	v_mfma_f32_16x16x32_bf16 v[102:105], v[194:197], v[166:169], v[102:105]
	v_mfma_f32_16x16x32_bf16 v[98:101], v[202:205], v[166:169], v[98:101]
	v_mfma_f32_16x16x32_bf16 v[86:89], v[194:197], v[176:179], v[86:89]
	v_mfma_f32_16x16x32_bf16 v[82:85], v[202:205], v[176:179], v[82:85]
	v_mfma_f32_16x16x32_bf16 v[70:73], v[194:197], v[184:187], v[70:73]
	v_mfma_f32_16x16x32_bf16 v[66:69], v[202:205], v[184:187], v[66:69]
	v_mfma_f32_16x16x32_bf16 v[118:121], v[198:201], v[162:165], v[118:121]
	v_mfma_f32_16x16x32_bf16 v[114:117], v[206:209], v[162:165], v[114:117]
	v_mfma_f32_16x16x32_bf16 v[102:105], v[198:201], v[172:175], v[102:105]
	v_mfma_f32_16x16x32_bf16 v[98:101], v[206:209], v[172:175], v[98:101]
	v_mfma_f32_16x16x32_bf16 v[86:89], v[198:201], v[180:183], v[86:89]
	v_mfma_f32_16x16x32_bf16 v[82:85], v[206:209], v[180:183], v[82:85]
	v_mfma_f32_16x16x32_bf16 v[70:73], v[198:201], v[190:193], v[70:73]
	v_mfma_f32_16x16x32_bf16 v[66:69], v[206:209], v[190:193], v[66:69]
	s_mov_b32 m0, s60
	v_lshl_add_u64 v[210:211], v[214:215], 0, s[40:41]
	s_barrier
	ds_read_b128 v[158:161], v171 offset:49152
	ds_read_b128 v[162:165], v171 offset:50176
	ds_read_b128 v[166:169], v171 offset:51200
	ds_read_b128 v[172:175], v171 offset:52224
	ds_read_b128 v[176:179], v171 offset:53248
	ds_read_b128 v[180:183], v171 offset:54272
	ds_read_b128 v[184:187], v171 offset:55296
	ds_read_b128 v[190:193], v171 offset:56320
	global_load_lds_dwordx4 v[210:211], off
	s_mov_b32 m0, s61
	v_lshl_add_u64 v[210:211], v[216:217], 0, s[40:41]
	global_load_lds_dwordx4 v[210:211], off
	s_barrier
	s_waitcnt lgkmcnt(0)
	v_mfma_f32_16x16x32_bf16 v[62:65], v[130:133], v[158:161], v[62:65]
	v_mfma_f32_16x16x32_bf16 v[58:61], v[138:141], v[158:161], v[58:61]
	v_mfma_f32_16x16x32_bf16 v[46:49], v[130:133], v[166:169], v[46:49]
	v_mfma_f32_16x16x32_bf16 v[42:45], v[138:141], v[166:169], v[42:45]
	v_mfma_f32_16x16x32_bf16 v[30:33], v[130:133], v[176:179], v[30:33]
	v_mfma_f32_16x16x32_bf16 v[26:29], v[138:141], v[176:179], v[26:29]
	v_mfma_f32_16x16x32_bf16 v[14:17], v[130:133], v[184:187], v[14:17]
	v_mfma_f32_16x16x32_bf16 v[10:13], v[138:141], v[184:187], v[10:13]
	v_mfma_f32_16x16x32_bf16 v[62:65], v[134:137], v[162:165], v[62:65]
	v_mfma_f32_16x16x32_bf16 v[58:61], v[142:145], v[162:165], v[58:61]
	v_mfma_f32_16x16x32_bf16 v[46:49], v[134:137], v[172:175], v[46:49]
	v_mfma_f32_16x16x32_bf16 v[42:45], v[142:145], v[172:175], v[42:45]
	v_mfma_f32_16x16x32_bf16 v[30:33], v[134:137], v[180:183], v[30:33]
	v_mfma_f32_16x16x32_bf16 v[26:29], v[142:145], v[180:183], v[26:29]
	v_mfma_f32_16x16x32_bf16 v[14:17], v[134:137], v[190:193], v[14:17]
	v_mfma_f32_16x16x32_bf16 v[10:13], v[142:145], v[190:193], v[10:13]
	s_barrier
	s_add_u32 s90, s90, 0x40080
	s_addc_u32 s91, s91, 0
	s_add_i32 s87, s92, s38
	s_mov_b32 m0, s87
	v_lshl_add_u64 v[130:131], s[90:91], 0, v[148:149]
	global_load_lds_dwordx4 v[130:131], off
	s_add_i32 m0, s87, 0x2000
	v_lshl_add_u64 v[130:131], s[90:91], 0, v[152:153]
	global_load_lds_dwordx4 v[130:131], off
	s_waitcnt vmcnt(6)
	s_barrier
	v_mfma_f32_16x16x32_bf16 v[54:57], v[194:197], v[158:161], v[54:57]
	v_mfma_f32_16x16x32_bf16 v[50:53], v[202:205], v[158:161], v[50:53]
	v_mfma_f32_16x16x32_bf16 v[38:41], v[194:197], v[166:169], v[38:41]
	v_mfma_f32_16x16x32_bf16 v[34:37], v[202:205], v[166:169], v[34:37]
	v_mfma_f32_16x16x32_bf16 v[22:25], v[194:197], v[176:179], v[22:25]
	v_mfma_f32_16x16x32_bf16 v[18:21], v[202:205], v[176:179], v[18:21]
	v_mfma_f32_16x16x32_bf16 v[6:9], v[194:197], v[184:187], v[6:9]
	v_mfma_f32_16x16x32_bf16 v[2:5], v[202:205], v[184:187], v[2:5]
	v_mfma_f32_16x16x32_bf16 v[54:57], v[198:201], v[162:165], v[54:57]
	v_mfma_f32_16x16x32_bf16 v[50:53], v[206:209], v[162:165], v[50:53]
	v_mfma_f32_16x16x32_bf16 v[38:41], v[198:201], v[172:175], v[38:41]
	v_mfma_f32_16x16x32_bf16 v[34:37], v[206:209], v[172:175], v[34:37]
	v_mfma_f32_16x16x32_bf16 v[22:25], v[198:201], v[180:183], v[22:25]
	v_mfma_f32_16x16x32_bf16 v[18:21], v[206:209], v[180:183], v[18:21]
	v_mfma_f32_16x16x32_bf16 v[6:9], v[198:201], v[190:193], v[6:9]
	v_mfma_f32_16x16x32_bf16 v[2:5], v[206:209], v[190:193], v[2:5]
	s_add_i32 s85, s85, 2
	s_add_u32 s88, s88, 0x100
	s_addc_u32 s89, s89, 0
	s_add_u32 s34, s34, 0x100
	s_addc_u32 s79, s79, 0
	s_cmp_gt_u32 s85, 13
	s_barrier
	s_cbranch_scc0 .LBB0_1209
	v_mov_b32_e32 v131, v252
	s_lshl_b32 s7, s86, 8
	v_and_b32_e32 v130, 63, v131
	v_or_b32_e32 v0, s72, v130
	v_lshrrev_b32_e32 v0, 1, v0
	v_and_or_b32 v132, v0, 63, s73
	v_add_u32_e32 v134, s7, v132
	v_ashrrev_i32_e32 v135, 31, v134
	v_and_b32_e32 v142, 1, v131
	v_lshlrev_b64 v[134:135], 6, v[134:135]
	v_lshl_add_u64 v[134:135], s[82:83], 0, v[134:135]
	v_lshlrev_b32_e32 v0, 5, v142
	v_lshl_add_u64 v[138:139], v[134:135], 0, v[0:1]
	global_load_dwordx4 v[134:137], v[138:139], off
	s_nop 0
	global_load_dwordx4 v[138:141], v[138:139], off offset:16
	v_lshlrev_b32_e32 v0, 2, v130
	v_cmp_eq_u32_e32 vcc, 0, v142
	s_waitcnt vmcnt(0)
	v_add_f32_e32 v133, v134, v135
	v_add_f32_e32 v134, v136, v137
	v_add_f32_e32 v135, v138, v139
	v_add_f32_e32 v136, v140, v141
	v_add_f32_e32 v133, v133, v134
	v_add_f32_e32 v134, v135, v136
	v_add_f32_e32 v133, v133, v134
	v_xor_b32_e32 v134, 4, v0
	ds_bpermute_b32 v134, v134, v133
	s_and_saveexec_b64 s[22:23], vcc
	s_cbranch_execz .LBB0_1212
	s_waitcnt lgkmcnt(0)
	v_add_f32_e32 v133, v133, v134
	v_fmamk_f32 v133, v133, 0x3a800000, v224
	s_mov_b32 s13, 0x800000
	v_mul_f32_e32 v134, 0x4b800000, v133
	v_cmp_gt_f32_e32 vcc, s13, v133
	v_lshl_add_u32 v132, v132, 2, 0
	v_add_u32_e32 v132, 0x20000, v132
	v_cndmask_b32_e32 v133, v133, v134, vcc
	v_rsq_f32_e32 v133, v133
	s_nop 0
	v_mul_f32_e32 v134, 0x45800000, v133
	v_cndmask_b32_e32 v133, v133, v134, vcc
	ds_write_b32 v132, v133
